# early ring-counter reads (fast poll path) + no store drain before the P1/P9 inter-tile barrier
# speedup vs baseline: 1.0161x; 1.0065x over previous
; DEVINL float sigm(float x) { return 1.f / (1.f + __expf(-x)); }
; template <int EPI, bool GATHER>
; DEVINL void gemm_tile(const Params& p, const u16* __restrict__ A, int lda, const int* __restrict__ rowidx,
;                       const u16* __restrict__ Bt, int ldb, int K, int brow, int bcol, int orow, int ocol) {
;     ...
;   const int row0 = orow + wr * 64 + fq * 4;
;   const int col0 = ocol + wc * 32 + fr;
;   const bool odd = (fr & 1) != 0;
;   const int colp = col0 - (odd ? 1 : 0);
; #pragma unroll
;   for (int ai = 0; ai < 2; ++ai)
; #pragma unroll
;     for (int m = 0; m < 4; ++m) {
;       const int rA = row0 + ai * HALF + m * 16 + (odd ? 2 : 0);
;       float gate[2] = {0.f, 0.f};
;       if (EPI == EPI_MOE2) { gate[0] = ((const float*)(ws + O_SELG))[rA]; gate[1] = ((const float*)(ws + O_SELG))[rA + 1]; }
; #pragma unroll
;       for (int bj = 0; bj < (EPI == EPI_HID ? 1 : 2); ++bj)
; #pragma unroll
;         for (int n = 0; n < 2; ++n) {
;           const int cc = bj * HALF + n * 16;
;           f32x4 v = acc[ai][bj][m][n];
;           if (EPI == EPI_HID) {
; #pragma unroll
;             for (int j = 0; j < 4; ++j) { const float a1 = acc[ai][0][m][n][j], a3 = acc[ai][1][m][n][j]; v[j] = a1 * sigm(a1) * a3; }
;           }
;           float lo[2], hi[2];
;           xchg_pairs(v, odd, lo, hi);
; #pragma unroll
;           for (int k = 0; k < 2; ++k) {
;             const unsigned row = (unsigned)(rA + k);
;             if (EPI == EPI_HID) {
;               *(unsigned*)(ws + O_HID + (row * 1024u + (unsigned)(colp + cc)) * 2u) = pk2(lo[k], hi[k]);
;             } else if (EPI == EPI_COLS) {
;               *(unsigned*)(ws + O_COLS + (row * (unsigned)NCP + (unsigned)(colp + cc)) * 2u) = pk2(lo[k], hi[k]);
.LBB0_223:
	s_or_b64 exec, exec, s[6:7]
	v_and_b32_e32 v130, 1, v141
	v_add_u32_e32 v128, s48, v145
	v_lshlrev_b32_e32 v129, 2, v144
	v_lshlrev_b32_e32 v131, 1, v130
	v_or3_b32 v128, v128, v131, v129
	v_or_b32_e32 v129, s78, v143
	v_cmp_eq_u32_e32 vcc, 0, v130
	v_sub_u32_e32 v129, v129, v130
	s_movk_i32 s4, 0x2a00
	v_cndmask_b32_e32 v130, v124, v126, vcc
	v_cndmask_b32_e32 v131, v125, v127, vcc
	v_lshl_add_u32 v129, v142, 5, v129
	v_mov_b32_dpp v130, v130 quad_perm:[1,0,3,2] row_mask:0xf bank_mask:0xf bound_ctrl:1
	v_cndmask_b32_e32 v124, v130, v124, vcc
	v_cndmask_b32_e32 v126, v126, v130, vcc
	v_mov_b32_dpp v131, v131 quad_perm:[1,0,3,2] row_mask:0xf bank_mask:0xf bound_ctrl:1
	v_cvt_pk_bf16_f32 v124, v124, v126
	v_mul_lo_u32 v126, v128, s4
	v_cndmask_b32_e32 v125, v131, v125, vcc
	v_cndmask_b32_e32 v127, v127, v131, vcc
	v_add_lshl_u32 v128, v126, v129, 1
	global_store_dword v128, v124, s[0:1]
	v_cvt_pk_bf16_f32 v124, v125, v127
	v_add_u32_e32 v125, 0x2a00, v126
	v_add_lshl_u32 v127, v125, v129, 1
	global_store_dword v127, v124, s[0:1]
	v_cndmask_b32_e32 v124, v116, v118, vcc
	v_cndmask_b32_e32 v127, v117, v119, vcc
	s_nop 0
	v_mov_b32_dpp v124, v124 quad_perm:[1,0,3,2] row_mask:0xf bank_mask:0xf bound_ctrl:1
	v_mov_b32_dpp v127, v127 quad_perm:[1,0,3,2] row_mask:0xf bank_mask:0xf bound_ctrl:1
	v_cndmask_b32_e32 v116, v124, v116, vcc
	v_cndmask_b32_e32 v118, v118, v124, vcc
	v_add_u32_e32 v124, 16, v129
	v_cndmask_b32_e32 v117, v127, v117, vcc
	v_cndmask_b32_e32 v119, v119, v127, vcc
	v_cvt_pk_bf16_f32 v116, v116, v118
	v_add_lshl_u32 v118, v126, v124, 1
	global_store_dword v118, v116, s[0:1]
	v_cvt_pk_bf16_f32 v116, v117, v119
	v_add_lshl_u32 v117, v125, v124, 1
	global_store_dword v117, v116, s[0:1]
	v_cndmask_b32_e32 v117, v120, v122, vcc
	v_cndmask_b32_e32 v118, v121, v123, vcc
	v_add_u32_e32 v116, 0x80, v129
	v_mov_b32_dpp v117, v117 quad_perm:[1,0,3,2] row_mask:0xf bank_mask:0xf bound_ctrl:1
	v_mov_b32_dpp v118, v118 quad_perm:[1,0,3,2] row_mask:0xf bank_mask:0xf bound_ctrl:1
	v_cndmask_b32_e32 v119, v117, v120, vcc
	v_cndmask_b32_e32 v117, v122, v117, vcc
	v_cndmask_b32_e32 v120, v118, v121, vcc
	v_cndmask_b32_e32 v118, v123, v118, vcc
	v_cvt_pk_bf16_f32 v117, v119, v117
	v_add_lshl_u32 v119, v126, v116, 1
	global_store_dword v119, v117, s[0:1]
	v_cvt_pk_bf16_f32 v117, v120, v118
	v_add_lshl_u32 v118, v125, v116, 1
	global_store_dword v118, v117, s[0:1]
	v_cndmask_b32_e32 v117, v112, v114, vcc
	v_cndmask_b32_e32 v118, v113, v115, vcc
	s_nop 0
	v_mov_b32_dpp v117, v117 quad_perm:[1,0,3,2] row_mask:0xf bank_mask:0xf bound_ctrl:1
	v_mov_b32_dpp v118, v118 quad_perm:[1,0,3,2] row_mask:0xf bank_mask:0xf bound_ctrl:1
	v_cndmask_b32_e32 v112, v117, v112, vcc
	v_cndmask_b32_e32 v114, v114, v117, vcc
	v_add_u32_e32 v117, 0x90, v129
	v_cndmask_b32_e32 v113, v118, v113, vcc
	v_cndmask_b32_e32 v115, v115, v118, vcc
	v_cvt_pk_bf16_f32 v112, v112, v114
	v_add_lshl_u32 v114, v126, v117, 1
	global_store_dword v114, v112, s[0:1]
	v_cvt_pk_bf16_f32 v112, v113, v115
	v_add_lshl_u32 v113, v125, v117, 1
	global_store_dword v113, v112, s[0:1]
	v_cndmask_b32_e32 v112, v108, v110, vcc
	v_cndmask_b32_e32 v113, v109, v111, vcc
	s_nop 0
	v_mov_b32_dpp v112, v112 quad_perm:[1,0,3,2] row_mask:0xf bank_mask:0xf bound_ctrl:1
	v_cndmask_b32_e32 v108, v112, v108, vcc
	v_cndmask_b32_e32 v110, v110, v112, vcc
	v_mov_b32_dpp v113, v113 quad_perm:[1,0,3,2] row_mask:0xf bank_mask:0xf bound_ctrl:1
	v_cvt_pk_bf16_f32 v108, v108, v110
	v_add_u32_e32 v110, 0x2a000, v126
	v_cndmask_b32_e32 v109, v113, v109, vcc
	v_cndmask_b32_e32 v111, v111, v113, vcc
	v_add_lshl_u32 v112, v110, v129, 1
	global_store_dword v112, v108, s[0:1]
	v_cvt_pk_bf16_f32 v108, v109, v111
	v_add_u32_e32 v109, 0x2ca00, v126
	v_add_lshl_u32 v111, v109, v129, 1
	global_store_dword v111, v108, s[0:1]
	v_cndmask_b32_e32 v108, v100, v102, vcc
	v_cndmask_b32_e32 v111, v101, v103, vcc
	s_nop 0
	v_mov_b32_dpp v108, v108 quad_perm:[1,0,3,2] row_mask:0xf bank_mask:0xf bound_ctrl:1
	v_mov_b32_dpp v111, v111 quad_perm:[1,0,3,2] row_mask:0xf bank_mask:0xf bound_ctrl:1
	v_cndmask_b32_e32 v100, v108, v100, vcc
	v_cndmask_b32_e32 v102, v102, v108, vcc
	v_cndmask_b32_e32 v101, v111, v101, vcc
	v_cndmask_b32_e32 v103, v103, v111, vcc
	v_cvt_pk_bf16_f32 v100, v100, v102
	v_add_lshl_u32 v102, v110, v124, 1
	global_store_dword v102, v100, s[0:1]
	v_cvt_pk_bf16_f32 v100, v101, v103
	v_add_lshl_u32 v101, v109, v124, 1
	global_store_dword v101, v100, s[0:1]
	v_cndmask_b32_e32 v100, v104, v106, vcc
	v_cndmask_b32_e32 v101, v105, v107, vcc
	s_nop 0
	v_mov_b32_dpp v100, v100 quad_perm:[1,0,3,2] row_mask:0xf bank_mask:0xf bound_ctrl:1
	v_mov_b32_dpp v101, v101 quad_perm:[1,0,3,2] row_mask:0xf bank_mask:0xf bound_ctrl:1
	v_cndmask_b32_e32 v102, v100, v104, vcc
	v_cndmask_b32_e32 v100, v106, v100, vcc
	v_cndmask_b32_e32 v103, v101, v105, vcc
	v_cndmask_b32_e32 v101, v107, v101, vcc
	v_cvt_pk_bf16_f32 v100, v102, v100
	v_add_lshl_u32 v102, v110, v116, 1
	global_store_dword v102, v100, s[0:1]
	v_cvt_pk_bf16_f32 v100, v103, v101
	v_add_lshl_u32 v101, v109, v116, 1
	global_store_dword v101, v100, s[0:1]
	v_cndmask_b32_e32 v100, v96, v98, vcc
	v_cndmask_b32_e32 v101, v97, v99, vcc
	s_nop 0
	v_mov_b32_dpp v100, v100 quad_perm:[1,0,3,2] row_mask:0xf bank_mask:0xf bound_ctrl:1
	v_mov_b32_dpp v101, v101 quad_perm:[1,0,3,2] row_mask:0xf bank_mask:0xf bound_ctrl:1
	v_cndmask_b32_e32 v96, v100, v96, vcc
	v_cndmask_b32_e32 v98, v98, v100, vcc
	v_cndmask_b32_e32 v97, v101, v97, vcc
	v_cndmask_b32_e32 v99, v99, v101, vcc
	v_cvt_pk_bf16_f32 v96, v96, v98
	v_add_lshl_u32 v98, v110, v117, 1
	global_store_dword v98, v96, s[0:1]
; DEVINL float sigm(float x) { return 1.f / (1.f + __expf(-x)); }
; template <int EPI, bool GATHER>
; DEVINL void gemm_tile(const Params& p, const u16* __restrict__ A, int lda, const int* __restrict__ rowidx,
;                       const u16* __restrict__ Bt, int ldb, int K, int brow, int bcol, int orow, int ocol) {
;     ...
;   const int row0 = orow + wr * 64 + fq * 4;
;   const int col0 = ocol + wc * 32 + fr;
;   const bool odd = (fr & 1) != 0;
;   const int colp = col0 - (odd ? 1 : 0);
; #pragma unroll
;   for (int ai = 0; ai < 2; ++ai)
; #pragma unroll
;     for (int m = 0; m < 4; ++m) {
;       const int rA = row0 + ai * HALF + m * 16 + (odd ? 2 : 0);
;       float gate[2] = {0.f, 0.f};
;       if (EPI == EPI_MOE2) { gate[0] = ((const float*)(ws + O_SELG))[rA]; gate[1] = ((const float*)(ws + O_SELG))[rA + 1]; }
; #pragma unroll
;       for (int bj = 0; bj < (EPI == EPI_HID ? 1 : 2); ++bj)
; #pragma unroll
;         for (int n = 0; n < 2; ++n) {
;           const int cc = bj * HALF + n * 16;
;           f32x4 v = acc[ai][bj][m][n];
;           if (EPI == EPI_HID) {
; #pragma unroll
;             for (int j = 0; j < 4; ++j) { const float a1 = acc[ai][0][m][n][j], a3 = acc[ai][1][m][n][j]; v[j] = a1 * sigm(a1) * a3; }
;           }
;           float lo[2], hi[2];
;           xchg_pairs(v, odd, lo, hi);
; #pragma unroll
;           for (int k = 0; k < 2; ++k) {
;             const unsigned row = (unsigned)(rA + k);
;             if (EPI == EPI_HID) {
;               *(unsigned*)(ws + O_HID + (row * 1024u + (unsigned)(colp + cc)) * 2u) = pk2(lo[k], hi[k]);
;             } else if (EPI == EPI_COLS) {
;               *(unsigned*)(ws + O_COLS + (row * (unsigned)NCP + (unsigned)(colp + cc)) * 2u) = pk2(lo[k], hi[k]);
	v_cvt_pk_bf16_f32 v96, v97, v99
	v_add_lshl_u32 v97, v109, v117, 1
	global_store_dword v97, v96, s[0:1]
	v_cndmask_b32_e32 v96, v92, v94, vcc
	v_cndmask_b32_e32 v97, v93, v95, vcc
	s_nop 0
	v_mov_b32_dpp v96, v96 quad_perm:[1,0,3,2] row_mask:0xf bank_mask:0xf bound_ctrl:1
	v_cndmask_b32_e32 v92, v96, v92, vcc
	v_cndmask_b32_e32 v94, v94, v96, vcc
	v_mov_b32_dpp v97, v97 quad_perm:[1,0,3,2] row_mask:0xf bank_mask:0xf bound_ctrl:1
	v_cvt_pk_bf16_f32 v92, v92, v94
	v_add_u32_e32 v94, 0x54000, v126
	v_cndmask_b32_e32 v93, v97, v93, vcc
	v_cndmask_b32_e32 v95, v95, v97, vcc
	v_add_lshl_u32 v96, v94, v129, 1
	global_store_dword v96, v92, s[0:1]
	v_cvt_pk_bf16_f32 v92, v93, v95
	v_add_u32_e32 v93, 0x56a00, v126
	v_add_lshl_u32 v95, v93, v129, 1
	global_store_dword v95, v92, s[0:1]
	v_cndmask_b32_e32 v92, v84, v86, vcc
	v_cndmask_b32_e32 v95, v85, v87, vcc
	s_nop 0
	v_mov_b32_dpp v92, v92 quad_perm:[1,0,3,2] row_mask:0xf bank_mask:0xf bound_ctrl:1
	v_mov_b32_dpp v95, v95 quad_perm:[1,0,3,2] row_mask:0xf bank_mask:0xf bound_ctrl:1
	v_cndmask_b32_e32 v84, v92, v84, vcc
	v_cndmask_b32_e32 v86, v86, v92, vcc
	v_cndmask_b32_e32 v85, v95, v85, vcc
	v_cndmask_b32_e32 v87, v87, v95, vcc
	v_cvt_pk_bf16_f32 v84, v84, v86
	v_add_lshl_u32 v86, v94, v124, 1
	global_store_dword v86, v84, s[0:1]
	v_cvt_pk_bf16_f32 v84, v85, v87
	v_add_lshl_u32 v85, v93, v124, 1
	global_store_dword v85, v84, s[0:1]
	v_cndmask_b32_e32 v84, v88, v90, vcc
	v_cndmask_b32_e32 v85, v89, v91, vcc
	s_nop 0
	v_mov_b32_dpp v84, v84 quad_perm:[1,0,3,2] row_mask:0xf bank_mask:0xf bound_ctrl:1
	v_mov_b32_dpp v85, v85 quad_perm:[1,0,3,2] row_mask:0xf bank_mask:0xf bound_ctrl:1
	v_cndmask_b32_e32 v86, v84, v88, vcc
	v_cndmask_b32_e32 v84, v90, v84, vcc
	v_cndmask_b32_e32 v87, v85, v89, vcc
	v_cndmask_b32_e32 v85, v91, v85, vcc
	v_cvt_pk_bf16_f32 v84, v86, v84
	v_add_lshl_u32 v86, v94, v116, 1
	global_store_dword v86, v84, s[0:1]
	v_cvt_pk_bf16_f32 v84, v87, v85
	v_add_lshl_u32 v85, v93, v116, 1
	global_store_dword v85, v84, s[0:1]
	v_cndmask_b32_e32 v84, v80, v82, vcc
	v_cndmask_b32_e32 v85, v81, v83, vcc
	s_nop 0
	v_mov_b32_dpp v84, v84 quad_perm:[1,0,3,2] row_mask:0xf bank_mask:0xf bound_ctrl:1
	v_mov_b32_dpp v85, v85 quad_perm:[1,0,3,2] row_mask:0xf bank_mask:0xf bound_ctrl:1
	v_cndmask_b32_e32 v80, v84, v80, vcc
	v_cndmask_b32_e32 v82, v82, v84, vcc
	v_cndmask_b32_e32 v81, v85, v81, vcc
	v_cndmask_b32_e32 v83, v83, v85, vcc
	v_cvt_pk_bf16_f32 v80, v80, v82
	v_add_lshl_u32 v82, v94, v117, 1
	global_store_dword v82, v80, s[0:1]
	v_cvt_pk_bf16_f32 v80, v81, v83
	v_add_lshl_u32 v81, v93, v117, 1
	global_store_dword v81, v80, s[0:1]
	v_cndmask_b32_e32 v80, v76, v78, vcc
	v_cndmask_b32_e32 v81, v77, v79, vcc
	s_nop 0
	v_mov_b32_dpp v80, v80 quad_perm:[1,0,3,2] row_mask:0xf bank_mask:0xf bound_ctrl:1
	v_cndmask_b32_e32 v76, v80, v76, vcc
	v_cndmask_b32_e32 v78, v78, v80, vcc
	v_mov_b32_dpp v81, v81 quad_perm:[1,0,3,2] row_mask:0xf bank_mask:0xf bound_ctrl:1
	v_cvt_pk_bf16_f32 v76, v76, v78
	v_add_u32_e32 v78, 0x7e000, v126
	v_cndmask_b32_e32 v77, v81, v77, vcc
	v_cndmask_b32_e32 v79, v79, v81, vcc
	v_add_lshl_u32 v80, v78, v129, 1
	global_store_dword v80, v76, s[0:1]
	v_cvt_pk_bf16_f32 v76, v77, v79
	v_add_u32_e32 v77, 0x80a00, v126
	v_add_lshl_u32 v79, v77, v129, 1
	global_store_dword v79, v76, s[0:1]
	v_cndmask_b32_e32 v76, v68, v70, vcc
	v_cndmask_b32_e32 v79, v69, v71, vcc
	s_nop 0
	v_mov_b32_dpp v76, v76 quad_perm:[1,0,3,2] row_mask:0xf bank_mask:0xf bound_ctrl:1
	v_mov_b32_dpp v79, v79 quad_perm:[1,0,3,2] row_mask:0xf bank_mask:0xf bound_ctrl:1
	v_cndmask_b32_e32 v68, v76, v68, vcc
	v_cndmask_b32_e32 v70, v70, v76, vcc
	v_cndmask_b32_e32 v69, v79, v69, vcc
	v_cndmask_b32_e32 v71, v71, v79, vcc
	v_cvt_pk_bf16_f32 v68, v68, v70
	v_add_lshl_u32 v70, v78, v124, 1
	global_store_dword v70, v68, s[0:1]
	v_cvt_pk_bf16_f32 v68, v69, v71
	v_add_lshl_u32 v69, v77, v124, 1
	global_store_dword v69, v68, s[0:1]
	v_cndmask_b32_e32 v68, v72, v74, vcc
	v_cndmask_b32_e32 v69, v73, v75, vcc
	s_nop 0
	v_mov_b32_dpp v68, v68 quad_perm:[1,0,3,2] row_mask:0xf bank_mask:0xf bound_ctrl:1
	v_mov_b32_dpp v69, v69 quad_perm:[1,0,3,2] row_mask:0xf bank_mask:0xf bound_ctrl:1
	v_cndmask_b32_e32 v70, v68, v72, vcc
	v_cndmask_b32_e32 v68, v74, v68, vcc
	v_cndmask_b32_e32 v71, v69, v73, vcc
	v_cndmask_b32_e32 v69, v75, v69, vcc
	v_cvt_pk_bf16_f32 v68, v70, v68
	v_add_lshl_u32 v70, v78, v116, 1
	global_store_dword v70, v68, s[0:1]
	v_cvt_pk_bf16_f32 v68, v71, v69
	v_add_lshl_u32 v69, v77, v116, 1
	global_store_dword v69, v68, s[0:1]
	v_cndmask_b32_e32 v68, v60, v62, vcc
	v_cndmask_b32_e32 v69, v61, v63, vcc
	s_nop 0
	v_mov_b32_dpp v68, v68 quad_perm:[1,0,3,2] row_mask:0xf bank_mask:0xf bound_ctrl:1
	v_mov_b32_dpp v69, v69 quad_perm:[1,0,3,2] row_mask:0xf bank_mask:0xf bound_ctrl:1
	v_cndmask_b32_e32 v60, v68, v60, vcc
	v_cndmask_b32_e32 v62, v62, v68, vcc
	v_cndmask_b32_e32 v61, v69, v61, vcc
	v_cndmask_b32_e32 v63, v63, v69, vcc
	v_cvt_pk_bf16_f32 v60, v60, v62
	v_add_lshl_u32 v62, v78, v117, 1
	global_store_dword v62, v60, s[0:1]
	v_cvt_pk_bf16_f32 v60, v61, v63
	v_add_lshl_u32 v61, v77, v117, 1
	global_store_dword v61, v60, s[0:1]
	v_cndmask_b32_e32 v60, v64, v66, vcc
	v_cndmask_b32_e32 v61, v65, v67, vcc
	s_nop 0
	v_mov_b32_dpp v60, v60 quad_perm:[1,0,3,2] row_mask:0xf bank_mask:0xf bound_ctrl:1
	v_cndmask_b32_e32 v62, v60, v64, vcc
	v_cndmask_b32_e32 v60, v66, v60, vcc
	v_mov_b32_dpp v61, v61 quad_perm:[1,0,3,2] row_mask:0xf bank_mask:0xf bound_ctrl:1
	v_cvt_pk_bf16_f32 v60, v62, v60
	v_add_u32_e32 v62, 0x150000, v126
	v_cndmask_b32_e32 v63, v61, v65, vcc
	v_cndmask_b32_e32 v61, v67, v61, vcc
	v_add_lshl_u32 v64, v62, v129, 1
; DEVINL float sigm(float x) { return 1.f / (1.f + __expf(-x)); }
; template <int EPI, bool GATHER>
; DEVINL void gemm_tile(const Params& p, const u16* __restrict__ A, int lda, const int* __restrict__ rowidx,
;                       const u16* __restrict__ Bt, int ldb, int K, int brow, int bcol, int orow, int ocol) {
;     ...
;   const int row0 = orow + wr * 64 + fq * 4;
;   const int col0 = ocol + wc * 32 + fr;
;   const bool odd = (fr & 1) != 0;
;   const int colp = col0 - (odd ? 1 : 0);
; #pragma unroll
;   for (int ai = 0; ai < 2; ++ai)
; #pragma unroll
;     for (int m = 0; m < 4; ++m) {
;       const int rA = row0 + ai * HALF + m * 16 + (odd ? 2 : 0);
;       float gate[2] = {0.f, 0.f};
;       if (EPI == EPI_MOE2) { gate[0] = ((const float*)(ws + O_SELG))[rA]; gate[1] = ((const float*)(ws + O_SELG))[rA + 1]; }
; #pragma unroll
;       for (int bj = 0; bj < (EPI == EPI_HID ? 1 : 2); ++bj)
; #pragma unroll
;         for (int n = 0; n < 2; ++n) {
;           const int cc = bj * HALF + n * 16;
;           f32x4 v = acc[ai][bj][m][n];
;           if (EPI == EPI_HID) {
; #pragma unroll
;             for (int j = 0; j < 4; ++j) { const float a1 = acc[ai][0][m][n][j], a3 = acc[ai][1][m][n][j]; v[j] = a1 * sigm(a1) * a3; }
;           }
;           float lo[2], hi[2];
;           xchg_pairs(v, odd, lo, hi);
; #pragma unroll
;           for (int k = 0; k < 2; ++k) {
;             const unsigned row = (unsigned)(rA + k);
;             if (EPI == EPI_HID) {
;               *(unsigned*)(ws + O_HID + (row * 1024u + (unsigned)(colp + cc)) * 2u) = pk2(lo[k], hi[k]);
;             } else if (EPI == EPI_COLS) {
;               *(unsigned*)(ws + O_COLS + (row * (unsigned)NCP + (unsigned)(colp + cc)) * 2u) = pk2(lo[k], hi[k]);
	global_store_dword v64, v60, s[0:1]
	v_cvt_pk_bf16_f32 v60, v63, v61
	v_add_u32_e32 v61, 0x152a00, v126
	v_add_lshl_u32 v63, v61, v129, 1
	global_store_dword v63, v60, s[0:1]
	v_cndmask_b32_e32 v60, v52, v54, vcc
	v_cndmask_b32_e32 v63, v53, v55, vcc
	s_nop 0
	v_mov_b32_dpp v60, v60 quad_perm:[1,0,3,2] row_mask:0xf bank_mask:0xf bound_ctrl:1
	v_mov_b32_dpp v63, v63 quad_perm:[1,0,3,2] row_mask:0xf bank_mask:0xf bound_ctrl:1
	v_cndmask_b32_e32 v52, v60, v52, vcc
	v_cndmask_b32_e32 v54, v54, v60, vcc
	v_cndmask_b32_e32 v53, v63, v53, vcc
	v_cndmask_b32_e32 v55, v55, v63, vcc
	v_cvt_pk_bf16_f32 v52, v52, v54
	v_add_lshl_u32 v54, v62, v124, 1
	global_store_dword v54, v52, s[0:1]
	v_cvt_pk_bf16_f32 v52, v53, v55
	v_add_lshl_u32 v53, v61, v124, 1
	global_store_dword v53, v52, s[0:1]
	v_cndmask_b32_e32 v52, v56, v58, vcc
	v_cndmask_b32_e32 v53, v57, v59, vcc
	s_nop 0
	v_mov_b32_dpp v52, v52 quad_perm:[1,0,3,2] row_mask:0xf bank_mask:0xf bound_ctrl:1
	v_mov_b32_dpp v53, v53 quad_perm:[1,0,3,2] row_mask:0xf bank_mask:0xf bound_ctrl:1
	v_cndmask_b32_e32 v54, v52, v56, vcc
	v_cndmask_b32_e32 v52, v58, v52, vcc
	v_cndmask_b32_e32 v55, v53, v57, vcc
	v_cndmask_b32_e32 v53, v59, v53, vcc
	v_cvt_pk_bf16_f32 v52, v54, v52
	v_add_lshl_u32 v54, v62, v116, 1
	global_store_dword v54, v52, s[0:1]
	v_cvt_pk_bf16_f32 v52, v55, v53
	v_add_lshl_u32 v53, v61, v116, 1
	global_store_dword v53, v52, s[0:1]
	v_cndmask_b32_e32 v52, v48, v50, vcc
	v_cndmask_b32_e32 v53, v49, v51, vcc
	s_nop 0
	v_mov_b32_dpp v52, v52 quad_perm:[1,0,3,2] row_mask:0xf bank_mask:0xf bound_ctrl:1
	v_mov_b32_dpp v53, v53 quad_perm:[1,0,3,2] row_mask:0xf bank_mask:0xf bound_ctrl:1
	v_cndmask_b32_e32 v48, v52, v48, vcc
	v_cndmask_b32_e32 v50, v50, v52, vcc
	v_cndmask_b32_e32 v49, v53, v49, vcc
	v_cndmask_b32_e32 v51, v51, v53, vcc
	v_cvt_pk_bf16_f32 v48, v48, v50
	v_add_lshl_u32 v50, v62, v117, 1
	global_store_dword v50, v48, s[0:1]
	v_cvt_pk_bf16_f32 v48, v49, v51
	v_add_lshl_u32 v49, v61, v117, 1
	global_store_dword v49, v48, s[0:1]
	v_cndmask_b32_e32 v48, v44, v46, vcc
	v_cndmask_b32_e32 v49, v45, v47, vcc
	s_nop 0
	v_mov_b32_dpp v48, v48 quad_perm:[1,0,3,2] row_mask:0xf bank_mask:0xf bound_ctrl:1
	v_cndmask_b32_e32 v44, v48, v44, vcc
	v_cndmask_b32_e32 v46, v46, v48, vcc
	v_mov_b32_dpp v49, v49 quad_perm:[1,0,3,2] row_mask:0xf bank_mask:0xf bound_ctrl:1
	v_cvt_pk_bf16_f32 v44, v44, v46
	v_add_u32_e32 v46, 0x17a000, v126
	v_cndmask_b32_e32 v45, v49, v45, vcc
	v_cndmask_b32_e32 v47, v47, v49, vcc
	v_add_lshl_u32 v48, v46, v129, 1
	global_store_dword v48, v44, s[0:1]
	v_cvt_pk_bf16_f32 v44, v45, v47
	v_add_u32_e32 v45, 0x17ca00, v126
	v_add_lshl_u32 v47, v45, v129, 1
	global_store_dword v47, v44, s[0:1]
	v_cndmask_b32_e32 v44, v36, v38, vcc
	v_cndmask_b32_e32 v47, v37, v39, vcc
	s_nop 0
	v_mov_b32_dpp v44, v44 quad_perm:[1,0,3,2] row_mask:0xf bank_mask:0xf bound_ctrl:1
	v_mov_b32_dpp v47, v47 quad_perm:[1,0,3,2] row_mask:0xf bank_mask:0xf bound_ctrl:1
	v_cndmask_b32_e32 v36, v44, v36, vcc
	v_cndmask_b32_e32 v38, v38, v44, vcc
	v_cndmask_b32_e32 v37, v47, v37, vcc
	v_cndmask_b32_e32 v39, v39, v47, vcc
	v_cvt_pk_bf16_f32 v36, v36, v38
	v_add_lshl_u32 v38, v46, v124, 1
	global_store_dword v38, v36, s[0:1]
	v_cvt_pk_bf16_f32 v36, v37, v39
	v_add_lshl_u32 v37, v45, v124, 1
	global_store_dword v37, v36, s[0:1]
	v_cndmask_b32_e32 v36, v40, v42, vcc
	v_cndmask_b32_e32 v37, v41, v43, vcc
	s_nop 0
	v_mov_b32_dpp v36, v36 quad_perm:[1,0,3,2] row_mask:0xf bank_mask:0xf bound_ctrl:1
	v_mov_b32_dpp v37, v37 quad_perm:[1,0,3,2] row_mask:0xf bank_mask:0xf bound_ctrl:1
	v_cndmask_b32_e32 v38, v36, v40, vcc
	v_cndmask_b32_e32 v36, v42, v36, vcc
	v_cndmask_b32_e32 v39, v37, v41, vcc
	v_cndmask_b32_e32 v37, v43, v37, vcc
	v_cvt_pk_bf16_f32 v36, v38, v36
	v_add_lshl_u32 v38, v46, v116, 1
	global_store_dword v38, v36, s[0:1]
	v_cvt_pk_bf16_f32 v36, v39, v37
	v_add_lshl_u32 v37, v45, v116, 1
	global_store_dword v37, v36, s[0:1]
	v_cndmask_b32_e32 v36, v32, v34, vcc
	v_cndmask_b32_e32 v37, v33, v35, vcc
	s_nop 0
	v_mov_b32_dpp v36, v36 quad_perm:[1,0,3,2] row_mask:0xf bank_mask:0xf bound_ctrl:1
	v_mov_b32_dpp v37, v37 quad_perm:[1,0,3,2] row_mask:0xf bank_mask:0xf bound_ctrl:1
	v_cndmask_b32_e32 v32, v36, v32, vcc
	v_cndmask_b32_e32 v34, v34, v36, vcc
	v_cndmask_b32_e32 v33, v37, v33, vcc
	v_cndmask_b32_e32 v35, v35, v37, vcc
	v_cvt_pk_bf16_f32 v32, v32, v34
	v_add_lshl_u32 v34, v46, v117, 1
	global_store_dword v34, v32, s[0:1]
	v_cvt_pk_bf16_f32 v32, v33, v35
	v_add_lshl_u32 v33, v45, v117, 1
	global_store_dword v33, v32, s[0:1]
	v_cndmask_b32_e32 v32, v28, v30, vcc
	v_cndmask_b32_e32 v33, v29, v31, vcc
	s_nop 0
	v_mov_b32_dpp v32, v32 quad_perm:[1,0,3,2] row_mask:0xf bank_mask:0xf bound_ctrl:1
	v_cndmask_b32_e32 v28, v32, v28, vcc
	v_cndmask_b32_e32 v30, v30, v32, vcc
; template <int EPI, bool GATHER>
; DEVINL void gemm_tile(const Params& p, const u16* __restrict__ A, int lda, const int* __restrict__ rowidx,
;                       const u16* __restrict__ Bt, int ldb, int K, int brow, int bcol, int orow, int ocol) {
;     ...
; #pragma unroll
;   for (int ai = 0; ai < 2; ++ai)
; #pragma unroll
;     for (int m = 0; m < 4; ++m) {
;       const int rA = row0 + ai * HALF + m * 16 + (odd ? 2 : 0);
;       float gate[2] = {0.f, 0.f};
;       if (EPI == EPI_MOE2) { gate[0] = ((const float*)(ws + O_SELG))[rA]; gate[1] = ((const float*)(ws + O_SELG))[rA + 1]; }
; #pragma unroll
;       for (int bj = 0; bj < (EPI == EPI_HID ? 1 : 2); ++bj)
; #pragma unroll
;         for (int n = 0; n < 2; ++n) {
;           const int cc = bj * HALF + n * 16;
;           f32x4 v = acc[ai][bj][m][n];
;           if (EPI == EPI_HID) {
; #pragma unroll
;             for (int j = 0; j < 4; ++j) { const float a1 = acc[ai][0][m][n][j], a3 = acc[ai][1][m][n][j]; v[j] = a1 * sigm(a1) * a3; }
;           }
;           float lo[2], hi[2];
;           xchg_pairs(v, odd, lo, hi);
; #pragma unroll
;           for (int k = 0; k < 2; ++k) {
;             const unsigned row = (unsigned)(rA + k);
;             if (EPI == EPI_HID) {
;               *(unsigned*)(ws + O_HID + (row * 1024u + (unsigned)(colp + cc)) * 2u) = pk2(lo[k], hi[k]);
;             } else if (EPI == EPI_COLS) {
;               *(unsigned*)(ws + O_COLS + (row * (unsigned)NCP + (unsigned)(colp + cc)) * 2u) = pk2(lo[k], hi[k]);
;             } else if (EPI == EPI_MOE2) {
;               *(unsigned*)(ws + O_EO + (row * 2048u + (unsigned)(colp + cc)) * 2u) = pk2(gate[k] * lo[k], gate[k] * hi[k]);
;             } else if (EPI == EPI_M1) {
;               const unsigned g2 = *(const unsigned*)(ws + O_COLS + (row * (unsigned)NCP + (unsigned)(C_GG + colp + cc)) * 2u);
;               *(unsigned*)(ws + O_M1 + (row * 2048u + (unsigned)(colp + cc)) * 2u) = pk2(sigm(bflo(g2)) * lo[k], sigm(bfhi(g2)) * hi[k]);
;             } else if (EPI == EPI_MERGED) {
;               const unsigned g2 = *(const unsigned*)(ws + O_COLS + (row * (unsigned)NCP + (unsigned)(C_GR + colp + cc)) * 2u);
;               const unsigned m1 = *(const unsigned*)(ws + O_M1 + (row * 2048u + (unsigned)(colp + cc)) * 2u);
;               *(unsigned*)(ws + O_MERGED + (row * 2048u + (unsigned)(colp + cc)) * 2u) =
	v_mov_b32_dpp v33, v33 quad_perm:[1,0,3,2] row_mask:0xf bank_mask:0xf bound_ctrl:1
	v_cvt_pk_bf16_f32 v28, v28, v30
	v_add_u32_e32 v30, 0x1a4000, v126
	v_cndmask_b32_e32 v29, v33, v29, vcc
	v_cndmask_b32_e32 v31, v31, v33, vcc
	v_add_lshl_u32 v32, v30, v129, 1
	global_store_dword v32, v28, s[0:1]
	v_cvt_pk_bf16_f32 v28, v29, v31
	v_add_u32_e32 v29, 0x1a6a00, v126
	v_add_lshl_u32 v31, v29, v129, 1
	global_store_dword v31, v28, s[0:1]
	v_cndmask_b32_e32 v28, v20, v22, vcc
	v_cndmask_b32_e32 v31, v21, v23, vcc
	s_nop 0
	v_mov_b32_dpp v28, v28 quad_perm:[1,0,3,2] row_mask:0xf bank_mask:0xf bound_ctrl:1
	v_mov_b32_dpp v31, v31 quad_perm:[1,0,3,2] row_mask:0xf bank_mask:0xf bound_ctrl:1
	v_cndmask_b32_e32 v20, v28, v20, vcc
	v_cndmask_b32_e32 v22, v22, v28, vcc
	v_cndmask_b32_e32 v21, v31, v21, vcc
	v_cndmask_b32_e32 v23, v23, v31, vcc
	v_cvt_pk_bf16_f32 v20, v20, v22
	v_add_lshl_u32 v22, v30, v124, 1
	global_store_dword v22, v20, s[0:1]
	v_cvt_pk_bf16_f32 v20, v21, v23
	v_add_lshl_u32 v21, v29, v124, 1
	global_store_dword v21, v20, s[0:1]
	v_cndmask_b32_e32 v20, v24, v26, vcc
	v_cndmask_b32_e32 v21, v25, v27, vcc
	s_nop 0
	v_mov_b32_dpp v20, v20 quad_perm:[1,0,3,2] row_mask:0xf bank_mask:0xf bound_ctrl:1
	v_mov_b32_dpp v21, v21 quad_perm:[1,0,3,2] row_mask:0xf bank_mask:0xf bound_ctrl:1
	v_cndmask_b32_e32 v22, v20, v24, vcc
	v_cndmask_b32_e32 v20, v26, v20, vcc
	v_cndmask_b32_e32 v23, v21, v25, vcc
	v_cndmask_b32_e32 v21, v27, v21, vcc
	v_cvt_pk_bf16_f32 v20, v22, v20
	v_add_lshl_u32 v22, v30, v116, 1
	global_store_dword v22, v20, s[0:1]
	v_cvt_pk_bf16_f32 v20, v23, v21
	v_add_lshl_u32 v21, v29, v116, 1
	global_store_dword v21, v20, s[0:1]
	v_cndmask_b32_e32 v20, v16, v18, vcc
	v_cndmask_b32_e32 v21, v17, v19, vcc
	s_nop 0
	v_mov_b32_dpp v20, v20 quad_perm:[1,0,3,2] row_mask:0xf bank_mask:0xf bound_ctrl:1
	v_mov_b32_dpp v21, v21 quad_perm:[1,0,3,2] row_mask:0xf bank_mask:0xf bound_ctrl:1
	v_cndmask_b32_e32 v16, v20, v16, vcc
	v_cndmask_b32_e32 v18, v18, v20, vcc
	v_cndmask_b32_e32 v17, v21, v17, vcc
	v_cndmask_b32_e32 v19, v19, v21, vcc
	v_cvt_pk_bf16_f32 v16, v16, v18
	v_add_lshl_u32 v18, v30, v117, 1
	global_store_dword v18, v16, s[0:1]
	v_cvt_pk_bf16_f32 v16, v17, v19
	v_add_lshl_u32 v17, v29, v117, 1
	global_store_dword v17, v16, s[0:1]
	v_cndmask_b32_e32 v16, v12, v14, vcc
	v_cndmask_b32_e32 v17, v13, v15, vcc
	s_nop 0
	v_mov_b32_dpp v16, v16 quad_perm:[1,0,3,2] row_mask:0xf bank_mask:0xf bound_ctrl:1
	v_cndmask_b32_e32 v12, v16, v12, vcc
	v_cndmask_b32_e32 v14, v14, v16, vcc
	v_mov_b32_dpp v17, v17 quad_perm:[1,0,3,2] row_mask:0xf bank_mask:0xf bound_ctrl:1
	v_cvt_pk_bf16_f32 v12, v12, v14
	v_add_u32_e32 v14, 0x1ce000, v126
	v_cndmask_b32_e32 v13, v17, v13, vcc
	v_cndmask_b32_e32 v15, v15, v17, vcc
	v_add_lshl_u32 v16, v14, v129, 1
	global_store_dword v16, v12, s[0:1]
	v_cvt_pk_bf16_f32 v12, v13, v15
	v_add_u32_e32 v13, 0x1d0a00, v126
	v_add_lshl_u32 v15, v13, v129, 1
	global_store_dword v15, v12, s[0:1]
	v_cndmask_b32_e32 v12, v4, v6, vcc
	v_cndmask_b32_e32 v15, v5, v7, vcc
	s_nop 0
	v_mov_b32_dpp v12, v12 quad_perm:[1,0,3,2] row_mask:0xf bank_mask:0xf bound_ctrl:1
	v_mov_b32_dpp v15, v15 quad_perm:[1,0,3,2] row_mask:0xf bank_mask:0xf bound_ctrl:1
	v_cndmask_b32_e32 v4, v12, v4, vcc
	v_cndmask_b32_e32 v6, v6, v12, vcc
	v_cndmask_b32_e32 v5, v15, v5, vcc
	v_cndmask_b32_e32 v7, v7, v15, vcc
	v_cvt_pk_bf16_f32 v4, v4, v6
	v_add_lshl_u32 v6, v14, v124, 1
	global_store_dword v6, v4, s[0:1]
	v_cvt_pk_bf16_f32 v4, v5, v7
	v_add_lshl_u32 v5, v13, v124, 1
	global_store_dword v5, v4, s[0:1]
	v_cndmask_b32_e32 v4, v8, v10, vcc
	v_cndmask_b32_e32 v5, v9, v11, vcc
	s_nop 0
	v_mov_b32_dpp v4, v4 quad_perm:[1,0,3,2] row_mask:0xf bank_mask:0xf bound_ctrl:1
	v_mov_b32_dpp v5, v5 quad_perm:[1,0,3,2] row_mask:0xf bank_mask:0xf bound_ctrl:1
	v_cndmask_b32_e32 v6, v4, v8, vcc
	v_cndmask_b32_e32 v4, v10, v4, vcc
	v_cndmask_b32_e32 v7, v5, v9, vcc
	v_cndmask_b32_e32 v5, v11, v5, vcc
	v_cvt_pk_bf16_f32 v4, v6, v4
	v_add_lshl_u32 v6, v14, v116, 1
	global_store_dword v6, v4, s[0:1]
	v_cvt_pk_bf16_f32 v4, v7, v5
	v_add_lshl_u32 v5, v13, v116, 1
	global_store_dword v5, v4, s[0:1]
	v_cndmask_b32_e32 v4, v0, v2, vcc
	v_cndmask_b32_e32 v5, v1, v3, vcc
	s_nop 0
	v_mov_b32_dpp v4, v4 quad_perm:[1,0,3,2] row_mask:0xf bank_mask:0xf bound_ctrl:1
	v_mov_b32_dpp v5, v5 quad_perm:[1,0,3,2] row_mask:0xf bank_mask:0xf bound_ctrl:1
	v_cndmask_b32_e32 v0, v4, v0, vcc
	v_cndmask_b32_e32 v2, v2, v4, vcc
	v_cndmask_b32_e32 v1, v5, v1, vcc
	v_cndmask_b32_e32 v3, v3, v5, vcc
	v_cvt_pk_bf16_f32 v0, v0, v2
	v_add_lshl_u32 v2, v14, v117, 1
	global_store_dword v2, v0, s[0:1]
	v_cvt_pk_bf16_f32 v0, v1, v3
	v_add_lshl_u32 v1, v13, v117, 1
	global_store_dword v1, v0, s[0:1]
	s_add_i32 s47, s47, s94
	s_add_i32 s3, s3, s40
	s_add_i32 s41, s41, s42
	s_cmpk_lt_i32 s47, 0x500
	s_nop 0
	s_barrier
	s_cbranch_scc0 .LBB0_230

; DEVINL float sigm(float x) { return 1.f / (1.f + __expf(-x)); }
; template <int EPI, bool GATHER>
; DEVINL void gemm_tile(const Params& p, const u16* __restrict__ A, int lda, const int* __restrict__ rowidx,
;                       const u16* __restrict__ Bt, int ldb, int K, int brow, int bcol, int orow, int ocol) {
;     ...
;   const int row0 = orow + wr * 64 + fq * 4;
;   const int col0 = ocol + wc * 32 + fr;
;   const bool odd = (fr & 1) != 0;
;   const int colp = col0 - (odd ? 1 : 0);
; #pragma unroll
;   for (int ai = 0; ai < 2; ++ai)
; #pragma unroll
;     for (int m = 0; m < 4; ++m) {
;       const int rA = row0 + ai * HALF + m * 16 + (odd ? 2 : 0);
;       float gate[2] = {0.f, 0.f};
;       if (EPI == EPI_MOE2) { gate[0] = ((const float*)(ws + O_SELG))[rA]; gate[1] = ((const float*)(ws + O_SELG))[rA + 1]; }
; #pragma unroll
;       for (int bj = 0; bj < (EPI == EPI_HID ? 1 : 2); ++bj)
; #pragma unroll
;         for (int n = 0; n < 2; ++n) {
;           const int cc = bj * HALF + n * 16;
;           f32x4 v = acc[ai][bj][m][n];
;           if (EPI == EPI_HID) {
; #pragma unroll
;             for (int j = 0; j < 4; ++j) { const float a1 = acc[ai][0][m][n][j], a3 = acc[ai][1][m][n][j]; v[j] = a1 * sigm(a1) * a3; }
;           }
;           float lo[2], hi[2];
;           xchg_pairs(v, odd, lo, hi);
; #pragma unroll
;           for (int k = 0; k < 2; ++k) {
;             const unsigned row = (unsigned)(rA + k);
;             if (EPI == EPI_HID) {
;               *(unsigned*)(ws + O_HID + (row * 1024u + (unsigned)(colp + cc)) * 2u) = pk2(lo[k], hi[k]);
.LBB0_969:
	s_or_b64 exec, exec, s[6:7]
	v_mul_f32_e32 v128, 0xbfb8aa3b, v120
	v_exp_f32_e32 v128, v128
	v_and_b32_e32 v129, 1, v145
	v_lshl_or_b32 v130, s48, 7, v149
	v_sub_u32_e32 v130, v130, v129
	v_add_f32_e32 v131, 1.0, v128
	v_div_scale_f32 v132, s[6:7], v131, v131, 1.0
	v_rcp_f32_e32 v133, v132
	v_lshlrev_b32_e32 v128, 6, v148
	v_lshl_add_u32 v128, v130, 1, v128
	v_fma_f32 v130, -v132, v133, 1.0
	v_fmac_f32_e32 v133, v130, v133
	v_div_scale_f32 v130, vcc, 1.0, v131, 1.0
	v_mul_f32_e32 v134, v130, v133
	v_fma_f32 v135, -v132, v134, v130
	v_fmac_f32_e32 v134, v135, v133
	v_mul_f32_e32 v135, 0xbfb8aa3b, v121
	v_exp_f32_e32 v135, v135
	v_fma_f32 v130, -v132, v134, v130
	v_div_fmas_f32 v130, v130, v133, v134
	v_div_fixup_f32 v130, v130, v131, 1.0
	v_add_f32_e32 v132, 1.0, v135
	v_div_scale_f32 v133, s[6:7], v132, v132, 1.0
	v_rcp_f32_e32 v134, v133
	v_mul_f32_e32 v120, v120, v130
	v_mul_f32_e32 v120, v120, v124
	v_fma_f32 v124, -v133, v134, 1.0
	v_fmac_f32_e32 v134, v124, v134
	v_div_scale_f32 v124, vcc, 1.0, v132, 1.0
	v_mul_f32_e32 v130, v124, v134
	v_fma_f32 v131, -v133, v130, v124
	v_fmac_f32_e32 v130, v131, v134
	v_mul_f32_e32 v131, 0xbfb8aa3b, v122
	v_exp_f32_e32 v131, v131
	v_fma_f32 v124, -v133, v130, v124
	v_div_fmas_f32 v124, v124, v134, v130
	v_div_fixup_f32 v124, v124, v132, 1.0
	v_add_f32_e32 v130, 1.0, v131
	v_div_scale_f32 v131, s[6:7], v130, v130, 1.0
	v_rcp_f32_e32 v133, v131
	v_mul_f32_e32 v121, v121, v124
	v_mul_f32_e32 v121, v121, v125
	v_fma_f32 v124, -v131, v133, 1.0
	v_fmac_f32_e32 v133, v124, v133
	v_div_scale_f32 v124, vcc, 1.0, v130, 1.0
	v_mul_f32_e32 v125, v124, v133
	v_fma_f32 v132, -v131, v125, v124
	v_fmac_f32_e32 v125, v132, v133
	v_mul_f32_e32 v132, 0xbfb8aa3b, v123
	v_exp_f32_e32 v132, v132
	v_fma_f32 v124, -v131, v125, v124
	v_div_fmas_f32 v124, v124, v133, v125
	v_div_fixup_f32 v124, v124, v130, 1.0
	v_add_f32_e32 v125, 1.0, v132
	v_div_scale_f32 v131, s[6:7], v125, v125, 1.0
	v_rcp_f32_e32 v132, v131
	v_mul_f32_e32 v122, v122, v124
	v_mul_f32_e32 v122, v122, v126
	v_cmp_eq_u32_e64 s[6:7], 0, v129
	v_fma_f32 v124, -v131, v132, 1.0
	v_fmac_f32_e32 v132, v124, v132
	v_div_scale_f32 v124, vcc, 1.0, v125, 1.0
	v_mul_f32_e32 v126, v124, v132
	v_fma_f32 v130, -v131, v126, v124
	v_fmac_f32_e32 v126, v130, v132
	v_fma_f32 v124, -v131, v126, v124
	v_div_fmas_f32 v124, v124, v132, v126
	v_div_fixup_f32 v124, v124, v125, 1.0
	v_mul_f32_e32 v123, v123, v124
	v_mul_f32_e32 v123, v123, v127
	v_cndmask_b32_e64 v124, v120, v122, s[6:7]
	v_cndmask_b32_e64 v125, v121, v123, s[6:7]
	s_nop 0
	v_mov_b32_dpp v124, v124 quad_perm:[1,0,3,2] row_mask:0xf bank_mask:0xf bound_ctrl:1
	v_mov_b32_dpp v125, v125 quad_perm:[1,0,3,2] row_mask:0xf bank_mask:0xf bound_ctrl:1
	v_cndmask_b32_e64 v120, v124, v120, s[6:7]
	v_cndmask_b32_e64 v122, v122, v124, s[6:7]
	v_cndmask_b32_e64 v121, v125, v121, s[6:7]
	v_cndmask_b32_e64 v123, v123, v125, s[6:7]
	v_cvt_pk_bf16_f32 v122, v120, v122
	v_lshlrev_b32_e32 v120, 13, v146
	v_lshlrev_b32_e32 v124, 12, v129
	v_add_lshl_u32 v125, s47, v147, 11
	v_or3_b32 v120, v125, v124, v120
	v_mul_f32_e32 v124, 0xbfb8aa3b, v112
	v_exp_f32_e32 v124, v124
	v_add_u32_e32 v125, v120, v128
	global_store_dword v125, v122, s[20:21]
	v_cvt_pk_bf16_f32 v121, v121, v123
	v_add_f32_e32 v122, 1.0, v124
	v_div_scale_f32 v123, s[38:39], v122, v122, 1.0
	v_rcp_f32_e32 v124, v123
	v_or_b32_e32 v125, 0x800, v120
	v_add_u32_e32 v126, v125, v128
	global_store_dword v126, v121, s[20:21]
	v_fma_f32 v121, -v123, v124, 1.0
	v_fmac_f32_e32 v124, v121, v124
	v_div_scale_f32 v121, vcc, 1.0, v122, 1.0
	v_mul_f32_e32 v126, v121, v124
	v_fma_f32 v127, -v123, v126, v121
	v_fmac_f32_e32 v126, v127, v124
	v_mul_f32_e32 v127, 0xbfb8aa3b, v113
	v_exp_f32_e32 v127, v127
	v_fma_f32 v121, -v123, v126, v121
	v_div_fmas_f32 v121, v121, v124, v126
	v_div_fixup_f32 v121, v121, v122, 1.0
	v_add_f32_e32 v123, 1.0, v127
	v_div_scale_f32 v124, s[38:39], v123, v123, 1.0
	v_rcp_f32_e32 v126, v124
	v_mul_f32_e32 v112, v112, v121
	v_mul_f32_e32 v112, v112, v116
	v_fma_f32 v116, -v124, v126, 1.0
	v_fmac_f32_e32 v126, v116, v126
	v_div_scale_f32 v116, vcc, 1.0, v123, 1.0
	v_mul_f32_e32 v121, v116, v126
	v_fma_f32 v122, -v124, v121, v116
	v_fmac_f32_e32 v121, v122, v126
	v_mul_f32_e32 v122, 0xbfb8aa3b, v114
	v_exp_f32_e32 v122, v122
	v_fma_f32 v116, -v124, v121, v116
	v_div_fmas_f32 v116, v116, v126, v121
	v_div_fixup_f32 v116, v116, v123, 1.0
	v_add_f32_e32 v121, 1.0, v122
	v_div_scale_f32 v122, s[38:39], v121, v121, 1.0
	v_rcp_f32_e32 v124, v122
	v_mul_f32_e32 v113, v113, v116
	v_mul_f32_e32 v113, v113, v117
	v_fma_f32 v116, -v122, v124, 1.0
	v_fmac_f32_e32 v124, v116, v124
	v_div_scale_f32 v116, vcc, 1.0, v121, 1.0
	v_mul_f32_e32 v117, v116, v124
	v_fma_f32 v123, -v122, v117, v116
	v_fmac_f32_e32 v117, v123, v124
	v_mul_f32_e32 v123, 0xbfb8aa3b, v115
	v_exp_f32_e32 v123, v123
	v_fma_f32 v116, -v122, v117, v116
	v_div_fmas_f32 v116, v116, v124, v117
	v_div_fixup_f32 v116, v116, v121, 1.0
	v_add_f32_e32 v117, 1.0, v123
	v_div_scale_f32 v122, s[38:39], v117, v117, 1.0
	v_rcp_f32_e32 v123, v122
	v_mul_f32_e32 v114, v114, v116
	v_mul_f32_e32 v114, v114, v118
	v_fma_f32 v116, -v122, v123, 1.0
	v_fmac_f32_e32 v123, v116, v123
	v_div_scale_f32 v116, vcc, 1.0, v117, 1.0
	v_mul_f32_e32 v118, v116, v123
	v_fma_f32 v121, -v122, v118, v116
	v_fmac_f32_e32 v118, v121, v123
	v_fma_f32 v116, -v122, v118, v116
	v_div_fmas_f32 v116, v116, v123, v118
	v_div_fixup_f32 v116, v116, v117, 1.0
	v_mul_f32_e32 v115, v115, v116
	v_mul_f32_e32 v115, v115, v119
	v_cndmask_b32_e64 v116, v112, v114, s[6:7]
	v_cndmask_b32_e64 v117, v113, v115, s[6:7]
	s_nop 0
; DEVINL float sigm(float x) { return 1.f / (1.f + __expf(-x)); }
; template <int EPI, bool GATHER>
; DEVINL void gemm_tile(const Params& p, const u16* __restrict__ A, int lda, const int* __restrict__ rowidx,
;                       const u16* __restrict__ Bt, int ldb, int K, int brow, int bcol, int orow, int ocol) {
;     ...
;   const int row0 = orow + wr * 64 + fq * 4;
;   const int col0 = ocol + wc * 32 + fr;
;   const bool odd = (fr & 1) != 0;
;   const int colp = col0 - (odd ? 1 : 0);
; #pragma unroll
;   for (int ai = 0; ai < 2; ++ai)
; #pragma unroll
;     for (int m = 0; m < 4; ++m) {
;       const int rA = row0 + ai * HALF + m * 16 + (odd ? 2 : 0);
;       float gate[2] = {0.f, 0.f};
;       if (EPI == EPI_MOE2) { gate[0] = ((const float*)(ws + O_SELG))[rA]; gate[1] = ((const float*)(ws + O_SELG))[rA + 1]; }
; #pragma unroll
;       for (int bj = 0; bj < (EPI == EPI_HID ? 1 : 2); ++bj)
; #pragma unroll
;         for (int n = 0; n < 2; ++n) {
;           const int cc = bj * HALF + n * 16;
;           f32x4 v = acc[ai][bj][m][n];
;           if (EPI == EPI_HID) {
; #pragma unroll
;             for (int j = 0; j < 4; ++j) { const float a1 = acc[ai][0][m][n][j], a3 = acc[ai][1][m][n][j]; v[j] = a1 * sigm(a1) * a3; }
;           }
;           float lo[2], hi[2];
;           xchg_pairs(v, odd, lo, hi);
; #pragma unroll
;           for (int k = 0; k < 2; ++k) {
;             const unsigned row = (unsigned)(rA + k);
;             if (EPI == EPI_HID) {
;               *(unsigned*)(ws + O_HID + (row * 1024u + (unsigned)(colp + cc)) * 2u) = pk2(lo[k], hi[k]);
	v_mov_b32_dpp v116, v116 quad_perm:[1,0,3,2] row_mask:0xf bank_mask:0xf bound_ctrl:1
	v_mov_b32_dpp v117, v117 quad_perm:[1,0,3,2] row_mask:0xf bank_mask:0xf bound_ctrl:1
	v_cndmask_b32_e64 v118, v116, v112, s[6:7]
	v_cndmask_b32_e64 v114, v114, v116, s[6:7]
	v_add_u32_e32 v112, 32, v128
	v_cndmask_b32_e64 v113, v117, v113, s[6:7]
	v_cndmask_b32_e64 v115, v115, v117, s[6:7]
	v_cvt_pk_bf16_f32 v114, v118, v114
	v_add_u32_e32 v116, v120, v112
	global_store_dword v116, v114, s[20:21]
	v_cvt_pk_bf16_f32 v113, v113, v115
	v_add_u32_e32 v114, v125, v112
	global_store_dword v114, v113, s[20:21]
	v_mul_f32_e32 v113, 0xbfb8aa3b, v104
	v_exp_f32_e32 v113, v113
	v_mul_f32_e32 v114, 0xbfb8aa3b, v105
	v_exp_f32_e32 v114, v114
	v_add_f32_e32 v113, 1.0, v113
	v_div_scale_f32 v115, s[38:39], v113, v113, 1.0
	v_rcp_f32_e32 v116, v115
	v_div_scale_f32 v117, vcc, 1.0, v113, 1.0
	v_add_f32_e32 v114, 1.0, v114
	v_fma_f32 v118, -v115, v116, 1.0
	v_fmac_f32_e32 v116, v118, v116
	v_mul_f32_e32 v118, v117, v116
	v_fma_f32 v119, -v115, v118, v117
	v_fmac_f32_e32 v118, v119, v116
	v_fma_f32 v115, -v115, v118, v117
	v_div_fmas_f32 v115, v115, v116, v118
	v_div_scale_f32 v116, s[38:39], v114, v114, 1.0
	v_rcp_f32_e32 v117, v116
	v_div_fixup_f32 v113, v115, v113, 1.0
	v_mul_f32_e32 v104, v104, v113
	v_mul_f32_e32 v104, v104, v108
	v_fma_f32 v108, -v116, v117, 1.0
	v_fmac_f32_e32 v117, v108, v117
	v_div_scale_f32 v108, vcc, 1.0, v114, 1.0
	v_mul_f32_e32 v113, v108, v117
	v_fma_f32 v115, -v116, v113, v108
	v_fmac_f32_e32 v113, v115, v117
	v_mul_f32_e32 v115, 0xbfb8aa3b, v106
	v_exp_f32_e32 v115, v115
	v_fma_f32 v108, -v116, v113, v108
	v_div_fmas_f32 v108, v108, v117, v113
	v_div_fixup_f32 v108, v108, v114, 1.0
	v_add_f32_e32 v113, 1.0, v115
	v_div_scale_f32 v115, s[38:39], v113, v113, 1.0
	v_rcp_f32_e32 v116, v115
	v_mul_f32_e32 v105, v105, v108
	v_mul_f32_e32 v105, v105, v109
	v_fma_f32 v108, -v115, v116, 1.0
	v_fmac_f32_e32 v116, v108, v116
	v_div_scale_f32 v108, vcc, 1.0, v113, 1.0
	v_mul_f32_e32 v109, v108, v116
	v_fma_f32 v114, -v115, v109, v108
	v_fmac_f32_e32 v109, v114, v116
	v_mul_f32_e32 v114, 0xbfb8aa3b, v107
	v_exp_f32_e32 v114, v114
	v_fma_f32 v108, -v115, v109, v108
	v_div_fmas_f32 v108, v108, v116, v109
	v_div_fixup_f32 v108, v108, v113, 1.0
	v_add_f32_e32 v109, 1.0, v114
	v_div_scale_f32 v114, s[38:39], v109, v109, 1.0
	v_rcp_f32_e32 v115, v114
	v_mul_f32_e32 v106, v106, v108
	v_mul_f32_e32 v106, v106, v110
	v_fma_f32 v108, -v114, v115, 1.0
	v_fmac_f32_e32 v115, v108, v115
	v_div_scale_f32 v108, vcc, 1.0, v109, 1.0
	v_mul_f32_e32 v110, v108, v115
	v_fma_f32 v113, -v114, v110, v108
	v_fmac_f32_e32 v110, v113, v115
	v_fma_f32 v108, -v114, v110, v108
	v_div_fmas_f32 v108, v108, v115, v110
	v_div_fixup_f32 v108, v108, v109, 1.0
	v_mul_f32_e32 v107, v107, v108
	v_cndmask_b32_e64 v108, v104, v106, s[6:7]
	v_mul_f32_e32 v107, v107, v111
	v_cndmask_b32_e64 v109, v105, v107, s[6:7]
	v_mov_b32_dpp v108, v108 quad_perm:[1,0,3,2] row_mask:0xf bank_mask:0xf bound_ctrl:1
	v_cndmask_b32_e64 v104, v108, v104, s[6:7]
	v_cndmask_b32_e64 v106, v106, v108, s[6:7]
	v_mul_f32_e32 v108, 0xbfb8aa3b, v96
	v_exp_f32_e32 v108, v108
	v_mov_b32_dpp v109, v109 quad_perm:[1,0,3,2] row_mask:0xf bank_mask:0xf bound_ctrl:1
	v_cvt_pk_bf16_f32 v104, v104, v106
	v_or_b32_e32 v106, 0x8000, v120
	v_cndmask_b32_e64 v105, v109, v105, s[6:7]
	v_cndmask_b32_e64 v107, v107, v109, s[6:7]
	v_add_u32_e32 v109, v106, v128
	global_store_dword v109, v104, s[20:21]
	v_cvt_pk_bf16_f32 v104, v105, v107
	v_add_f32_e32 v105, 1.0, v108
	v_div_scale_f32 v107, s[38:39], v105, v105, 1.0
	v_rcp_f32_e32 v108, v107
	v_or_b32_e32 v109, 0x8800, v120
	v_add_u32_e32 v110, v109, v128
	global_store_dword v110, v104, s[20:21]
	v_fma_f32 v104, -v107, v108, 1.0
	v_fmac_f32_e32 v108, v104, v108
	v_div_scale_f32 v104, vcc, 1.0, v105, 1.0
	v_mul_f32_e32 v110, v104, v108
	v_fma_f32 v111, -v107, v110, v104
	v_fmac_f32_e32 v110, v111, v108
	v_mul_f32_e32 v111, 0xbfb8aa3b, v97
	v_exp_f32_e32 v111, v111
	v_fma_f32 v104, -v107, v110, v104
	v_div_fmas_f32 v104, v104, v108, v110
	v_div_fixup_f32 v104, v104, v105, 1.0
	v_add_f32_e32 v107, 1.0, v111
	v_div_scale_f32 v108, s[38:39], v107, v107, 1.0
	v_rcp_f32_e32 v110, v108
	v_mul_f32_e32 v96, v96, v104
	v_mul_f32_e32 v96, v96, v100
	v_fma_f32 v100, -v108, v110, 1.0
	v_fmac_f32_e32 v110, v100, v110
	v_div_scale_f32 v100, vcc, 1.0, v107, 1.0
	v_mul_f32_e32 v104, v100, v110
	v_fma_f32 v105, -v108, v104, v100
	v_fmac_f32_e32 v104, v105, v110
	v_mul_f32_e32 v105, 0xbfb8aa3b, v98
	v_exp_f32_e32 v105, v105
	v_fma_f32 v100, -v108, v104, v100
	v_div_fmas_f32 v100, v100, v110, v104
	v_div_fixup_f32 v100, v100, v107, 1.0
	v_add_f32_e32 v104, 1.0, v105
	v_div_scale_f32 v105, s[38:39], v104, v104, 1.0
	v_rcp_f32_e32 v108, v105
	v_mul_f32_e32 v97, v97, v100
	v_mul_f32_e32 v97, v97, v101
	v_fma_f32 v100, -v105, v108, 1.0
	v_fmac_f32_e32 v108, v100, v108
	v_div_scale_f32 v100, vcc, 1.0, v104, 1.0
	v_mul_f32_e32 v101, v100, v108
	v_fma_f32 v107, -v105, v101, v100
	v_fmac_f32_e32 v101, v107, v108
	v_mul_f32_e32 v107, 0xbfb8aa3b, v99
	v_exp_f32_e32 v107, v107
	v_fma_f32 v100, -v105, v101, v100
	v_div_fmas_f32 v100, v100, v108, v101
	v_div_fixup_f32 v100, v100, v104, 1.0
	v_add_f32_e32 v101, 1.0, v107
	v_div_scale_f32 v105, s[38:39], v101, v101, 1.0
	v_rcp_f32_e32 v107, v105
	v_mul_f32_e32 v98, v98, v100
	v_mul_f32_e32 v98, v98, v102
	v_fma_f32 v100, -v105, v107, 1.0
	v_fmac_f32_e32 v107, v100, v107
	v_div_scale_f32 v100, vcc, 1.0, v101, 1.0
	v_mul_f32_e32 v102, v100, v107
	v_fma_f32 v104, -v105, v102, v100
	v_fmac_f32_e32 v102, v104, v107
	v_fma_f32 v100, -v105, v102, v100
	v_div_fmas_f32 v100, v100, v107, v102
; DEVINL float sigm(float x) { return 1.f / (1.f + __expf(-x)); }
; template <int EPI, bool GATHER>
; DEVINL void gemm_tile(const Params& p, const u16* __restrict__ A, int lda, const int* __restrict__ rowidx,
;                       const u16* __restrict__ Bt, int ldb, int K, int brow, int bcol, int orow, int ocol) {
;     ...
;   const int row0 = orow + wr * 64 + fq * 4;
;   const int col0 = ocol + wc * 32 + fr;
;   const bool odd = (fr & 1) != 0;
;   const int colp = col0 - (odd ? 1 : 0);
; #pragma unroll
;   for (int ai = 0; ai < 2; ++ai)
; #pragma unroll
;     for (int m = 0; m < 4; ++m) {
;       const int rA = row0 + ai * HALF + m * 16 + (odd ? 2 : 0);
;       float gate[2] = {0.f, 0.f};
;       if (EPI == EPI_MOE2) { gate[0] = ((const float*)(ws + O_SELG))[rA]; gate[1] = ((const float*)(ws + O_SELG))[rA + 1]; }
; #pragma unroll
;       for (int bj = 0; bj < (EPI == EPI_HID ? 1 : 2); ++bj)
; #pragma unroll
;         for (int n = 0; n < 2; ++n) {
;           const int cc = bj * HALF + n * 16;
;           f32x4 v = acc[ai][bj][m][n];
;           if (EPI == EPI_HID) {
; #pragma unroll
;             for (int j = 0; j < 4; ++j) { const float a1 = acc[ai][0][m][n][j], a3 = acc[ai][1][m][n][j]; v[j] = a1 * sigm(a1) * a3; }
;           }
;           float lo[2], hi[2];
;           xchg_pairs(v, odd, lo, hi);
; #pragma unroll
;           for (int k = 0; k < 2; ++k) {
;             const unsigned row = (unsigned)(rA + k);
;             if (EPI == EPI_HID) {
;               *(unsigned*)(ws + O_HID + (row * 1024u + (unsigned)(colp + cc)) * 2u) = pk2(lo[k], hi[k]);
	v_div_fixup_f32 v100, v100, v101, 1.0
	v_mul_f32_e32 v99, v99, v100
	v_mul_f32_e32 v99, v99, v103
	v_cndmask_b32_e64 v100, v96, v98, s[6:7]
	v_cndmask_b32_e64 v101, v97, v99, s[6:7]
	s_nop 0
	v_mov_b32_dpp v100, v100 quad_perm:[1,0,3,2] row_mask:0xf bank_mask:0xf bound_ctrl:1
	v_mov_b32_dpp v101, v101 quad_perm:[1,0,3,2] row_mask:0xf bank_mask:0xf bound_ctrl:1
	v_cndmask_b32_e64 v96, v100, v96, s[6:7]
	v_cndmask_b32_e64 v98, v98, v100, s[6:7]
	v_cndmask_b32_e64 v97, v101, v97, s[6:7]
	v_cndmask_b32_e64 v99, v99, v101, s[6:7]
	v_cvt_pk_bf16_f32 v96, v96, v98
	v_add_u32_e32 v98, v106, v112
	global_store_dword v98, v96, s[20:21]
	v_cvt_pk_bf16_f32 v96, v97, v99
	v_add_u32_e32 v97, v109, v112
	global_store_dword v97, v96, s[20:21]
	v_mul_f32_e32 v96, 0xbfb8aa3b, v88
	v_exp_f32_e32 v96, v96
	v_mul_f32_e32 v97, 0xbfb8aa3b, v89
	v_exp_f32_e32 v97, v97
	v_add_f32_e32 v96, 1.0, v96
	v_div_scale_f32 v98, s[38:39], v96, v96, 1.0
	v_rcp_f32_e32 v99, v98
	v_div_scale_f32 v100, vcc, 1.0, v96, 1.0
	v_add_f32_e32 v97, 1.0, v97
	v_fma_f32 v101, -v98, v99, 1.0
	v_fmac_f32_e32 v99, v101, v99
	v_mul_f32_e32 v101, v100, v99
	v_fma_f32 v102, -v98, v101, v100
	v_fmac_f32_e32 v101, v102, v99
	v_fma_f32 v98, -v98, v101, v100
	v_div_fmas_f32 v98, v98, v99, v101
	v_div_scale_f32 v99, s[38:39], v97, v97, 1.0
	v_rcp_f32_e32 v100, v99
	v_div_fixup_f32 v96, v98, v96, 1.0
	v_mul_f32_e32 v88, v88, v96
	v_mul_f32_e32 v88, v88, v92
	v_fma_f32 v92, -v99, v100, 1.0
	v_fmac_f32_e32 v100, v92, v100
	v_div_scale_f32 v92, vcc, 1.0, v97, 1.0
	v_mul_f32_e32 v96, v92, v100
	v_fma_f32 v98, -v99, v96, v92
	v_fmac_f32_e32 v96, v98, v100
	v_mul_f32_e32 v98, 0xbfb8aa3b, v90
	v_exp_f32_e32 v98, v98
	v_fma_f32 v92, -v99, v96, v92
	v_div_fmas_f32 v92, v92, v100, v96
	v_div_fixup_f32 v92, v92, v97, 1.0
	v_add_f32_e32 v96, 1.0, v98
	v_div_scale_f32 v98, s[38:39], v96, v96, 1.0
	v_rcp_f32_e32 v99, v98
	v_mul_f32_e32 v89, v89, v92
	v_mul_f32_e32 v89, v89, v93
	v_fma_f32 v92, -v98, v99, 1.0
	v_fmac_f32_e32 v99, v92, v99
	v_div_scale_f32 v92, vcc, 1.0, v96, 1.0
	v_mul_f32_e32 v93, v92, v99
	v_fma_f32 v97, -v98, v93, v92
	v_fmac_f32_e32 v93, v97, v99
	v_mul_f32_e32 v97, 0xbfb8aa3b, v91
	v_exp_f32_e32 v97, v97
	v_fma_f32 v92, -v98, v93, v92
	v_div_fmas_f32 v92, v92, v99, v93
	v_div_fixup_f32 v92, v92, v96, 1.0
	v_add_f32_e32 v93, 1.0, v97
	v_div_scale_f32 v97, s[38:39], v93, v93, 1.0
	v_rcp_f32_e32 v98, v97
	v_mul_f32_e32 v90, v90, v92
	v_mul_f32_e32 v90, v90, v94
	v_fma_f32 v92, -v97, v98, 1.0
	v_fmac_f32_e32 v98, v92, v98
	v_div_scale_f32 v92, vcc, 1.0, v93, 1.0
	v_mul_f32_e32 v94, v92, v98
	v_fma_f32 v96, -v97, v94, v92
	v_fmac_f32_e32 v94, v96, v98
	v_fma_f32 v92, -v97, v94, v92
	v_div_fmas_f32 v92, v92, v98, v94
	v_div_fixup_f32 v92, v92, v93, 1.0
	v_mul_f32_e32 v91, v91, v92
	v_cndmask_b32_e64 v92, v88, v90, s[6:7]
	v_mul_f32_e32 v91, v91, v95
	v_cndmask_b32_e64 v93, v89, v91, s[6:7]
	v_mov_b32_dpp v92, v92 quad_perm:[1,0,3,2] row_mask:0xf bank_mask:0xf bound_ctrl:1
	v_cndmask_b32_e64 v88, v92, v88, s[6:7]
	v_cndmask_b32_e64 v90, v90, v92, s[6:7]
	v_mul_f32_e32 v92, 0xbfb8aa3b, v80
	v_exp_f32_e32 v92, v92
	v_mov_b32_dpp v93, v93 quad_perm:[1,0,3,2] row_mask:0xf bank_mask:0xf bound_ctrl:1
	v_cvt_pk_bf16_f32 v88, v88, v90
	v_or_b32_e32 v90, 0x10000, v120
	v_cndmask_b32_e64 v89, v93, v89, s[6:7]
	v_cndmask_b32_e64 v91, v91, v93, s[6:7]
	v_add_u32_e32 v93, v90, v128
	global_store_dword v93, v88, s[20:21]
	v_cvt_pk_bf16_f32 v88, v89, v91
	v_add_f32_e32 v89, 1.0, v92
	v_div_scale_f32 v91, s[38:39], v89, v89, 1.0
	v_rcp_f32_e32 v92, v91
	v_or_b32_e32 v93, 0x10800, v120
	v_add_u32_e32 v94, v93, v128
	global_store_dword v94, v88, s[20:21]
	v_fma_f32 v88, -v91, v92, 1.0
	v_fmac_f32_e32 v92, v88, v92
	v_div_scale_f32 v88, vcc, 1.0, v89, 1.0
	v_mul_f32_e32 v94, v88, v92
	v_fma_f32 v95, -v91, v94, v88
	v_fmac_f32_e32 v94, v95, v92
	v_mul_f32_e32 v95, 0xbfb8aa3b, v81
	v_exp_f32_e32 v95, v95
	v_fma_f32 v88, -v91, v94, v88
	v_div_fmas_f32 v88, v88, v92, v94
	v_div_fixup_f32 v88, v88, v89, 1.0
	v_add_f32_e32 v91, 1.0, v95
	v_div_scale_f32 v92, s[38:39], v91, v91, 1.0
	v_rcp_f32_e32 v94, v92
	v_mul_f32_e32 v80, v80, v88
	v_mul_f32_e32 v80, v80, v84
	v_fma_f32 v84, -v92, v94, 1.0
	v_fmac_f32_e32 v94, v84, v94
	v_div_scale_f32 v84, vcc, 1.0, v91, 1.0
	v_mul_f32_e32 v88, v84, v94
	v_fma_f32 v89, -v92, v88, v84
	v_fmac_f32_e32 v88, v89, v94
	v_mul_f32_e32 v89, 0xbfb8aa3b, v82
	v_exp_f32_e32 v89, v89
	v_fma_f32 v84, -v92, v88, v84
	v_div_fmas_f32 v84, v84, v94, v88
	v_div_fixup_f32 v84, v84, v91, 1.0
	v_add_f32_e32 v88, 1.0, v89
	v_div_scale_f32 v89, s[38:39], v88, v88, 1.0
	v_rcp_f32_e32 v92, v89
	v_mul_f32_e32 v81, v81, v84
	v_mul_f32_e32 v81, v81, v85
	v_fma_f32 v84, -v89, v92, 1.0
	v_fmac_f32_e32 v92, v84, v92
	v_div_scale_f32 v84, vcc, 1.0, v88, 1.0
	v_mul_f32_e32 v85, v84, v92
	v_fma_f32 v91, -v89, v85, v84
	v_fmac_f32_e32 v85, v91, v92
	v_mul_f32_e32 v91, 0xbfb8aa3b, v83
	v_exp_f32_e32 v91, v91
	v_fma_f32 v84, -v89, v85, v84
	v_div_fmas_f32 v84, v84, v92, v85
	v_div_fixup_f32 v84, v84, v88, 1.0
	v_add_f32_e32 v85, 1.0, v91
	v_div_scale_f32 v89, s[38:39], v85, v85, 1.0
	v_rcp_f32_e32 v91, v89
	v_mul_f32_e32 v82, v82, v84
	v_mul_f32_e32 v82, v82, v86
	v_fma_f32 v84, -v89, v91, 1.0
	v_fmac_f32_e32 v91, v84, v91
	v_div_scale_f32 v84, vcc, 1.0, v85, 1.0
	v_mul_f32_e32 v86, v84, v91
	v_fma_f32 v88, -v89, v86, v84
	v_fmac_f32_e32 v86, v88, v91
	v_fma_f32 v84, -v89, v86, v84
	v_div_fmas_f32 v84, v84, v91, v86
	v_div_fixup_f32 v84, v84, v85, 1.0
	v_mul_f32_e32 v83, v83, v84
	v_mul_f32_e32 v83, v83, v87
	v_cndmask_b32_e64 v84, v80, v82, s[6:7]
	v_cndmask_b32_e64 v85, v81, v83, s[6:7]
	s_nop 0
; DEVINL float sigm(float x) { return 1.f / (1.f + __expf(-x)); }
; template <int EPI, bool GATHER>
; DEVINL void gemm_tile(const Params& p, const u16* __restrict__ A, int lda, const int* __restrict__ rowidx,
;                       const u16* __restrict__ Bt, int ldb, int K, int brow, int bcol, int orow, int ocol) {
;     ...
;   const int row0 = orow + wr * 64 + fq * 4;
;   const int col0 = ocol + wc * 32 + fr;
;   const bool odd = (fr & 1) != 0;
;   const int colp = col0 - (odd ? 1 : 0);
; #pragma unroll
;   for (int ai = 0; ai < 2; ++ai)
; #pragma unroll
;     for (int m = 0; m < 4; ++m) {
;       const int rA = row0 + ai * HALF + m * 16 + (odd ? 2 : 0);
;       float gate[2] = {0.f, 0.f};
;       if (EPI == EPI_MOE2) { gate[0] = ((const float*)(ws + O_SELG))[rA]; gate[1] = ((const float*)(ws + O_SELG))[rA + 1]; }
; #pragma unroll
;       for (int bj = 0; bj < (EPI == EPI_HID ? 1 : 2); ++bj)
; #pragma unroll
;         for (int n = 0; n < 2; ++n) {
;           const int cc = bj * HALF + n * 16;
;           f32x4 v = acc[ai][bj][m][n];
;           if (EPI == EPI_HID) {
; #pragma unroll
;             for (int j = 0; j < 4; ++j) { const float a1 = acc[ai][0][m][n][j], a3 = acc[ai][1][m][n][j]; v[j] = a1 * sigm(a1) * a3; }
;           }
;           float lo[2], hi[2];
;           xchg_pairs(v, odd, lo, hi);
; #pragma unroll
;           for (int k = 0; k < 2; ++k) {
;             const unsigned row = (unsigned)(rA + k);
;             if (EPI == EPI_HID) {
;               *(unsigned*)(ws + O_HID + (row * 1024u + (unsigned)(colp + cc)) * 2u) = pk2(lo[k], hi[k]);
	v_mov_b32_dpp v84, v84 quad_perm:[1,0,3,2] row_mask:0xf bank_mask:0xf bound_ctrl:1
	v_mov_b32_dpp v85, v85 quad_perm:[1,0,3,2] row_mask:0xf bank_mask:0xf bound_ctrl:1
	v_cndmask_b32_e64 v80, v84, v80, s[6:7]
	v_cndmask_b32_e64 v82, v82, v84, s[6:7]
	v_cndmask_b32_e64 v81, v85, v81, s[6:7]
	v_cndmask_b32_e64 v83, v83, v85, s[6:7]
	v_cvt_pk_bf16_f32 v80, v80, v82
	v_add_u32_e32 v82, v90, v112
	global_store_dword v82, v80, s[20:21]
	v_cvt_pk_bf16_f32 v80, v81, v83
	v_add_u32_e32 v81, v93, v112
	global_store_dword v81, v80, s[20:21]
	v_mul_f32_e32 v80, 0xbfb8aa3b, v72
	v_exp_f32_e32 v80, v80
	v_mul_f32_e32 v81, 0xbfb8aa3b, v73
	v_exp_f32_e32 v81, v81
	v_add_f32_e32 v80, 1.0, v80
	v_div_scale_f32 v82, s[38:39], v80, v80, 1.0
	v_rcp_f32_e32 v83, v82
	v_div_scale_f32 v84, vcc, 1.0, v80, 1.0
	v_add_f32_e32 v81, 1.0, v81
	v_fma_f32 v85, -v82, v83, 1.0
	v_fmac_f32_e32 v83, v85, v83
	v_mul_f32_e32 v85, v84, v83
	v_fma_f32 v86, -v82, v85, v84
	v_fmac_f32_e32 v85, v86, v83
	v_fma_f32 v82, -v82, v85, v84
	v_div_fmas_f32 v82, v82, v83, v85
	v_div_scale_f32 v83, s[38:39], v81, v81, 1.0
	v_rcp_f32_e32 v84, v83
	v_div_fixup_f32 v80, v82, v80, 1.0
	v_mul_f32_e32 v72, v72, v80
	v_mul_f32_e32 v72, v72, v76
	v_fma_f32 v76, -v83, v84, 1.0
	v_fmac_f32_e32 v84, v76, v84
	v_div_scale_f32 v76, vcc, 1.0, v81, 1.0
	v_mul_f32_e32 v80, v76, v84
	v_fma_f32 v82, -v83, v80, v76
	v_fmac_f32_e32 v80, v82, v84
	v_mul_f32_e32 v82, 0xbfb8aa3b, v74
	v_exp_f32_e32 v82, v82
	v_fma_f32 v76, -v83, v80, v76
	v_div_fmas_f32 v76, v76, v84, v80
	v_div_fixup_f32 v76, v76, v81, 1.0
	v_add_f32_e32 v80, 1.0, v82
	v_div_scale_f32 v82, s[38:39], v80, v80, 1.0
	v_rcp_f32_e32 v83, v82
	v_mul_f32_e32 v73, v73, v76
	v_mul_f32_e32 v73, v73, v77
	v_fma_f32 v76, -v82, v83, 1.0
	v_fmac_f32_e32 v83, v76, v83
	v_div_scale_f32 v76, vcc, 1.0, v80, 1.0
	v_mul_f32_e32 v77, v76, v83
	v_fma_f32 v81, -v82, v77, v76
	v_fmac_f32_e32 v77, v81, v83
	v_mul_f32_e32 v81, 0xbfb8aa3b, v75
	v_exp_f32_e32 v81, v81
	v_fma_f32 v76, -v82, v77, v76
	v_div_fmas_f32 v76, v76, v83, v77
	v_div_fixup_f32 v76, v76, v80, 1.0
	v_add_f32_e32 v77, 1.0, v81
	v_div_scale_f32 v81, s[38:39], v77, v77, 1.0
	v_rcp_f32_e32 v82, v81
	v_mul_f32_e32 v74, v74, v76
	v_mul_f32_e32 v74, v74, v78
	v_fma_f32 v76, -v81, v82, 1.0
	v_fmac_f32_e32 v82, v76, v82
	v_div_scale_f32 v76, vcc, 1.0, v77, 1.0
	v_mul_f32_e32 v78, v76, v82
	v_fma_f32 v80, -v81, v78, v76
	v_fmac_f32_e32 v78, v80, v82
	v_fma_f32 v76, -v81, v78, v76
	v_div_fmas_f32 v76, v76, v82, v78
	v_div_fixup_f32 v76, v76, v77, 1.0
	v_mul_f32_e32 v75, v75, v76
	v_cndmask_b32_e64 v76, v72, v74, s[6:7]
	v_mul_f32_e32 v75, v75, v79
	v_cndmask_b32_e64 v77, v73, v75, s[6:7]
	v_mov_b32_dpp v76, v76 quad_perm:[1,0,3,2] row_mask:0xf bank_mask:0xf bound_ctrl:1
	v_cndmask_b32_e64 v72, v76, v72, s[6:7]
	v_cndmask_b32_e64 v74, v74, v76, s[6:7]
	v_mul_f32_e32 v76, 0xbfb8aa3b, v64
	v_exp_f32_e32 v76, v76
	v_mov_b32_dpp v77, v77 quad_perm:[1,0,3,2] row_mask:0xf bank_mask:0xf bound_ctrl:1
	v_cvt_pk_bf16_f32 v72, v72, v74
	v_or_b32_e32 v74, 0x18000, v120
	v_cndmask_b32_e64 v73, v77, v73, s[6:7]
	v_cndmask_b32_e64 v75, v75, v77, s[6:7]
	v_add_u32_e32 v77, v74, v128
	global_store_dword v77, v72, s[20:21]
	v_cvt_pk_bf16_f32 v72, v73, v75
	v_add_f32_e32 v73, 1.0, v76
	v_div_scale_f32 v75, s[38:39], v73, v73, 1.0
	v_rcp_f32_e32 v76, v75
	v_or_b32_e32 v77, 0x18800, v120
	v_add_u32_e32 v78, v77, v128
	global_store_dword v78, v72, s[20:21]
	v_fma_f32 v72, -v75, v76, 1.0
	v_fmac_f32_e32 v76, v72, v76
	v_div_scale_f32 v72, vcc, 1.0, v73, 1.0
	v_mul_f32_e32 v78, v72, v76
	v_fma_f32 v79, -v75, v78, v72
	v_fmac_f32_e32 v78, v79, v76
	v_mul_f32_e32 v79, 0xbfb8aa3b, v65
	v_exp_f32_e32 v79, v79
	v_fma_f32 v72, -v75, v78, v72
	v_div_fmas_f32 v72, v72, v76, v78
	v_div_fixup_f32 v72, v72, v73, 1.0
	v_add_f32_e32 v75, 1.0, v79
	v_div_scale_f32 v76, s[38:39], v75, v75, 1.0
	v_rcp_f32_e32 v78, v76
	v_mul_f32_e32 v64, v64, v72
	v_mul_f32_e32 v64, v64, v68
	v_fma_f32 v68, -v76, v78, 1.0
	v_fmac_f32_e32 v78, v68, v78
	v_div_scale_f32 v68, vcc, 1.0, v75, 1.0
	v_mul_f32_e32 v72, v68, v78
	v_fma_f32 v73, -v76, v72, v68
	v_fmac_f32_e32 v72, v73, v78
	v_mul_f32_e32 v73, 0xbfb8aa3b, v66
	v_exp_f32_e32 v73, v73
	v_fma_f32 v68, -v76, v72, v68
	v_div_fmas_f32 v68, v68, v78, v72
	v_div_fixup_f32 v68, v68, v75, 1.0
	v_add_f32_e32 v72, 1.0, v73
	v_div_scale_f32 v73, s[38:39], v72, v72, 1.0
	v_rcp_f32_e32 v76, v73
	v_mul_f32_e32 v65, v65, v68
	v_mul_f32_e32 v65, v65, v69
	v_fma_f32 v68, -v73, v76, 1.0
	v_fmac_f32_e32 v76, v68, v76
	v_div_scale_f32 v68, vcc, 1.0, v72, 1.0
	v_mul_f32_e32 v69, v68, v76
	v_fma_f32 v75, -v73, v69, v68
	v_fmac_f32_e32 v69, v75, v76
	v_mul_f32_e32 v75, 0xbfb8aa3b, v67
	v_exp_f32_e32 v75, v75
	v_fma_f32 v68, -v73, v69, v68
	v_div_fmas_f32 v68, v68, v76, v69
	v_div_fixup_f32 v68, v68, v72, 1.0
	v_add_f32_e32 v69, 1.0, v75
	v_div_scale_f32 v73, s[38:39], v69, v69, 1.0
	v_rcp_f32_e32 v75, v73
	v_mul_f32_e32 v66, v66, v68
	v_mul_f32_e32 v66, v66, v70
	v_fma_f32 v68, -v73, v75, 1.0
	v_fmac_f32_e32 v75, v68, v75
	v_div_scale_f32 v68, vcc, 1.0, v69, 1.0
	v_mul_f32_e32 v70, v68, v75
	v_fma_f32 v72, -v73, v70, v68
	v_fmac_f32_e32 v70, v72, v75
	v_fma_f32 v68, -v73, v70, v68
	v_div_fmas_f32 v68, v68, v75, v70
	v_div_fixup_f32 v68, v68, v69, 1.0
	v_mul_f32_e32 v67, v67, v68
	v_mul_f32_e32 v67, v67, v71
	v_cndmask_b32_e64 v68, v64, v66, s[6:7]
	v_cndmask_b32_e64 v69, v65, v67, s[6:7]
	s_nop 0
	v_mov_b32_dpp v68, v68 quad_perm:[1,0,3,2] row_mask:0xf bank_mask:0xf bound_ctrl:1
	v_mov_b32_dpp v69, v69 quad_perm:[1,0,3,2] row_mask:0xf bank_mask:0xf bound_ctrl:1
	v_cndmask_b32_e64 v64, v68, v64, s[6:7]
	v_cndmask_b32_e64 v66, v66, v68, s[6:7]
; DEVINL float sigm(float x) { return 1.f / (1.f + __expf(-x)); }
; template <int EPI, bool GATHER>
; DEVINL void gemm_tile(const Params& p, const u16* __restrict__ A, int lda, const int* __restrict__ rowidx,
;                       const u16* __restrict__ Bt, int ldb, int K, int brow, int bcol, int orow, int ocol) {
;     ...
;   const int row0 = orow + wr * 64 + fq * 4;
;   const int col0 = ocol + wc * 32 + fr;
;   const bool odd = (fr & 1) != 0;
;   const int colp = col0 - (odd ? 1 : 0);
; #pragma unroll
;   for (int ai = 0; ai < 2; ++ai)
; #pragma unroll
;     for (int m = 0; m < 4; ++m) {
;       const int rA = row0 + ai * HALF + m * 16 + (odd ? 2 : 0);
;       float gate[2] = {0.f, 0.f};
;       if (EPI == EPI_MOE2) { gate[0] = ((const float*)(ws + O_SELG))[rA]; gate[1] = ((const float*)(ws + O_SELG))[rA + 1]; }
; #pragma unroll
;       for (int bj = 0; bj < (EPI == EPI_HID ? 1 : 2); ++bj)
; #pragma unroll
;         for (int n = 0; n < 2; ++n) {
;           const int cc = bj * HALF + n * 16;
;           f32x4 v = acc[ai][bj][m][n];
;           if (EPI == EPI_HID) {
; #pragma unroll
;             for (int j = 0; j < 4; ++j) { const float a1 = acc[ai][0][m][n][j], a3 = acc[ai][1][m][n][j]; v[j] = a1 * sigm(a1) * a3; }
;           }
;           float lo[2], hi[2];
;           xchg_pairs(v, odd, lo, hi);
; #pragma unroll
;           for (int k = 0; k < 2; ++k) {
;             const unsigned row = (unsigned)(rA + k);
;             if (EPI == EPI_HID) {
;               *(unsigned*)(ws + O_HID + (row * 1024u + (unsigned)(colp + cc)) * 2u) = pk2(lo[k], hi[k]);
	v_cndmask_b32_e64 v65, v69, v65, s[6:7]
	v_cndmask_b32_e64 v67, v67, v69, s[6:7]
	v_cvt_pk_bf16_f32 v64, v64, v66
	v_add_u32_e32 v66, v74, v112
	global_store_dword v66, v64, s[20:21]
	v_cvt_pk_bf16_f32 v64, v65, v67
	v_add_u32_e32 v65, v77, v112
	global_store_dword v65, v64, s[20:21]
	v_mul_f32_e32 v64, 0xbfb8aa3b, v56
	v_exp_f32_e32 v64, v64
	v_mul_f32_e32 v65, 0xbfb8aa3b, v57
	v_exp_f32_e32 v65, v65
	v_add_f32_e32 v64, 1.0, v64
	v_div_scale_f32 v66, s[38:39], v64, v64, 1.0
	v_rcp_f32_e32 v67, v66
	v_div_scale_f32 v68, vcc, 1.0, v64, 1.0
	v_add_f32_e32 v65, 1.0, v65
	v_fma_f32 v69, -v66, v67, 1.0
	v_fmac_f32_e32 v67, v69, v67
	v_mul_f32_e32 v69, v68, v67
	v_fma_f32 v70, -v66, v69, v68
	v_fmac_f32_e32 v69, v70, v67
	v_fma_f32 v66, -v66, v69, v68
	v_div_fmas_f32 v66, v66, v67, v69
	v_div_scale_f32 v67, s[38:39], v65, v65, 1.0
	v_rcp_f32_e32 v68, v67
	v_div_fixup_f32 v64, v66, v64, 1.0
	v_mul_f32_e32 v56, v56, v64
	v_mul_f32_e32 v56, v56, v60
	v_fma_f32 v60, -v67, v68, 1.0
	v_fmac_f32_e32 v68, v60, v68
	v_div_scale_f32 v60, vcc, 1.0, v65, 1.0
	v_mul_f32_e32 v64, v60, v68
	v_fma_f32 v66, -v67, v64, v60
	v_fmac_f32_e32 v64, v66, v68
	v_mul_f32_e32 v66, 0xbfb8aa3b, v58
	v_exp_f32_e32 v66, v66
	v_fma_f32 v60, -v67, v64, v60
	v_div_fmas_f32 v60, v60, v68, v64
	v_div_fixup_f32 v60, v60, v65, 1.0
	v_add_f32_e32 v64, 1.0, v66
	v_div_scale_f32 v66, s[38:39], v64, v64, 1.0
	v_rcp_f32_e32 v67, v66
	v_mul_f32_e32 v57, v57, v60
	v_mul_f32_e32 v57, v57, v61
	v_fma_f32 v60, -v66, v67, 1.0
	v_fmac_f32_e32 v67, v60, v67
	v_div_scale_f32 v60, vcc, 1.0, v64, 1.0
	v_mul_f32_e32 v61, v60, v67
	v_fma_f32 v65, -v66, v61, v60
	v_fmac_f32_e32 v61, v65, v67
	v_mul_f32_e32 v65, 0xbfb8aa3b, v59
	v_exp_f32_e32 v65, v65
	v_fma_f32 v60, -v66, v61, v60
	v_div_fmas_f32 v60, v60, v67, v61
	v_div_fixup_f32 v60, v60, v64, 1.0
	v_add_f32_e32 v61, 1.0, v65
	v_div_scale_f32 v65, s[38:39], v61, v61, 1.0
	v_rcp_f32_e32 v66, v65
	v_mul_f32_e32 v58, v58, v60
	v_mul_f32_e32 v58, v58, v62
	v_fma_f32 v60, -v65, v66, 1.0
	v_fmac_f32_e32 v66, v60, v66
	v_div_scale_f32 v60, vcc, 1.0, v61, 1.0
	v_mul_f32_e32 v62, v60, v66
	v_fma_f32 v64, -v65, v62, v60
	v_fmac_f32_e32 v62, v64, v66
	v_fma_f32 v60, -v65, v62, v60
	v_div_fmas_f32 v60, v60, v66, v62
	v_div_fixup_f32 v60, v60, v61, 1.0
	v_mul_f32_e32 v59, v59, v60
	v_cndmask_b32_e64 v60, v56, v58, s[6:7]
	v_mul_f32_e32 v59, v59, v63
	v_cndmask_b32_e64 v61, v57, v59, s[6:7]
	v_mov_b32_dpp v60, v60 quad_perm:[1,0,3,2] row_mask:0xf bank_mask:0xf bound_ctrl:1
	v_cndmask_b32_e64 v56, v60, v56, s[6:7]
	v_cndmask_b32_e64 v58, v58, v60, s[6:7]
	v_mul_f32_e32 v60, 0xbfb8aa3b, v48
	v_exp_f32_e32 v60, v60
	v_mov_b32_dpp v61, v61 quad_perm:[1,0,3,2] row_mask:0xf bank_mask:0xf bound_ctrl:1
	v_cvt_pk_bf16_f32 v56, v56, v58
	v_add_u32_e32 v58, 0x40000, v120
	v_cndmask_b32_e64 v57, v61, v57, s[6:7]
	v_cndmask_b32_e64 v59, v59, v61, s[6:7]
	v_add_u32_e32 v61, v58, v128
	global_store_dword v61, v56, s[20:21]
	v_cvt_pk_bf16_f32 v56, v57, v59
	v_add_f32_e32 v57, 1.0, v60
	v_div_scale_f32 v59, s[38:39], v57, v57, 1.0
	v_rcp_f32_e32 v60, v59
	v_add_u32_e32 v61, 0x40800, v120
	v_add_u32_e32 v62, v61, v128
	global_store_dword v62, v56, s[20:21]
	v_fma_f32 v56, -v59, v60, 1.0
	v_fmac_f32_e32 v60, v56, v60
	v_div_scale_f32 v56, vcc, 1.0, v57, 1.0
	v_mul_f32_e32 v62, v56, v60
	v_fma_f32 v63, -v59, v62, v56
	v_fmac_f32_e32 v62, v63, v60
	v_mul_f32_e32 v63, 0xbfb8aa3b, v49
	v_exp_f32_e32 v63, v63
	v_fma_f32 v56, -v59, v62, v56
	v_div_fmas_f32 v56, v56, v60, v62
	v_div_fixup_f32 v56, v56, v57, 1.0
	v_add_f32_e32 v59, 1.0, v63
	v_div_scale_f32 v60, s[38:39], v59, v59, 1.0
	v_rcp_f32_e32 v62, v60
	v_mul_f32_e32 v48, v48, v56
	v_mul_f32_e32 v48, v48, v52
	v_fma_f32 v52, -v60, v62, 1.0
	v_fmac_f32_e32 v62, v52, v62
	v_div_scale_f32 v52, vcc, 1.0, v59, 1.0
	v_mul_f32_e32 v56, v52, v62
	v_fma_f32 v57, -v60, v56, v52
	v_fmac_f32_e32 v56, v57, v62
	v_mul_f32_e32 v57, 0xbfb8aa3b, v50
	v_exp_f32_e32 v57, v57
	v_fma_f32 v52, -v60, v56, v52
	v_div_fmas_f32 v52, v52, v62, v56
	v_div_fixup_f32 v52, v52, v59, 1.0
	v_add_f32_e32 v56, 1.0, v57
	v_div_scale_f32 v57, s[38:39], v56, v56, 1.0
	v_rcp_f32_e32 v60, v57
	v_mul_f32_e32 v49, v49, v52
	v_mul_f32_e32 v49, v49, v53
	v_fma_f32 v52, -v57, v60, 1.0
	v_fmac_f32_e32 v60, v52, v60
	v_div_scale_f32 v52, vcc, 1.0, v56, 1.0
	v_mul_f32_e32 v53, v52, v60
	v_fma_f32 v59, -v57, v53, v52
	v_fmac_f32_e32 v53, v59, v60
	v_mul_f32_e32 v59, 0xbfb8aa3b, v51
	v_exp_f32_e32 v59, v59
	v_fma_f32 v52, -v57, v53, v52
	v_div_fmas_f32 v52, v52, v60, v53
	v_div_fixup_f32 v52, v52, v56, 1.0
	v_add_f32_e32 v53, 1.0, v59
	v_div_scale_f32 v57, s[38:39], v53, v53, 1.0
	v_rcp_f32_e32 v59, v57
	v_mul_f32_e32 v50, v50, v52
	v_mul_f32_e32 v50, v50, v54
	v_fma_f32 v52, -v57, v59, 1.0
	v_fmac_f32_e32 v59, v52, v59
	v_div_scale_f32 v52, vcc, 1.0, v53, 1.0
	v_mul_f32_e32 v54, v52, v59
	v_fma_f32 v56, -v57, v54, v52
	v_fmac_f32_e32 v54, v56, v59
	v_fma_f32 v52, -v57, v54, v52
	v_div_fmas_f32 v52, v52, v59, v54
	v_div_fixup_f32 v52, v52, v53, 1.0
	v_mul_f32_e32 v51, v51, v52
	v_mul_f32_e32 v51, v51, v55
	v_cndmask_b32_e64 v52, v48, v50, s[6:7]
	v_cndmask_b32_e64 v53, v49, v51, s[6:7]
	s_nop 0
	v_mov_b32_dpp v52, v52 quad_perm:[1,0,3,2] row_mask:0xf bank_mask:0xf bound_ctrl:1
	v_mov_b32_dpp v53, v53 quad_perm:[1,0,3,2] row_mask:0xf bank_mask:0xf bound_ctrl:1
	v_cndmask_b32_e64 v48, v52, v48, s[6:7]
	v_cndmask_b32_e64 v50, v50, v52, s[6:7]
	v_cndmask_b32_e64 v49, v53, v49, s[6:7]
	v_cndmask_b32_e64 v51, v51, v53, s[6:7]
	v_cvt_pk_bf16_f32 v48, v48, v50
	v_add_u32_e32 v50, v58, v112
	global_store_dword v50, v48, s[20:21]
	v_cvt_pk_bf16_f32 v48, v49, v51
	v_add_u32_e32 v49, v61, v112
; DEVINL float sigm(float x) { return 1.f / (1.f + __expf(-x)); }
; template <int EPI, bool GATHER>
; DEVINL void gemm_tile(const Params& p, const u16* __restrict__ A, int lda, const int* __restrict__ rowidx,
;                       const u16* __restrict__ Bt, int ldb, int K, int brow, int bcol, int orow, int ocol) {
;     ...
;   const int row0 = orow + wr * 64 + fq * 4;
;   const int col0 = ocol + wc * 32 + fr;
;   const bool odd = (fr & 1) != 0;
;   const int colp = col0 - (odd ? 1 : 0);
; #pragma unroll
;   for (int ai = 0; ai < 2; ++ai)
; #pragma unroll
;     for (int m = 0; m < 4; ++m) {
;       const int rA = row0 + ai * HALF + m * 16 + (odd ? 2 : 0);
;       float gate[2] = {0.f, 0.f};
;       if (EPI == EPI_MOE2) { gate[0] = ((const float*)(ws + O_SELG))[rA]; gate[1] = ((const float*)(ws + O_SELG))[rA + 1]; }
; #pragma unroll
;       for (int bj = 0; bj < (EPI == EPI_HID ? 1 : 2); ++bj)
; #pragma unroll
;         for (int n = 0; n < 2; ++n) {
;           const int cc = bj * HALF + n * 16;
;           f32x4 v = acc[ai][bj][m][n];
;           if (EPI == EPI_HID) {
; #pragma unroll
;             for (int j = 0; j < 4; ++j) { const float a1 = acc[ai][0][m][n][j], a3 = acc[ai][1][m][n][j]; v[j] = a1 * sigm(a1) * a3; }
;           }
;           float lo[2], hi[2];
;           xchg_pairs(v, odd, lo, hi);
; #pragma unroll
;           for (int k = 0; k < 2; ++k) {
;             const unsigned row = (unsigned)(rA + k);
;             if (EPI == EPI_HID) {
;               *(unsigned*)(ws + O_HID + (row * 1024u + (unsigned)(colp + cc)) * 2u) = pk2(lo[k], hi[k]);
	global_store_dword v49, v48, s[20:21]
	v_mul_f32_e32 v48, 0xbfb8aa3b, v40
	v_exp_f32_e32 v48, v48
	v_mul_f32_e32 v49, 0xbfb8aa3b, v41
	v_exp_f32_e32 v49, v49
	v_add_f32_e32 v48, 1.0, v48
	v_div_scale_f32 v50, s[38:39], v48, v48, 1.0
	v_rcp_f32_e32 v51, v50
	v_div_scale_f32 v52, vcc, 1.0, v48, 1.0
	v_add_f32_e32 v49, 1.0, v49
	v_fma_f32 v53, -v50, v51, 1.0
	v_fmac_f32_e32 v51, v53, v51
	v_mul_f32_e32 v53, v52, v51
	v_fma_f32 v54, -v50, v53, v52
	v_fmac_f32_e32 v53, v54, v51
	v_fma_f32 v50, -v50, v53, v52
	v_div_fmas_f32 v50, v50, v51, v53
	v_div_scale_f32 v51, s[38:39], v49, v49, 1.0
	v_rcp_f32_e32 v52, v51
	v_div_fixup_f32 v48, v50, v48, 1.0
	v_mul_f32_e32 v40, v40, v48
	v_mul_f32_e32 v40, v40, v44
	v_fma_f32 v44, -v51, v52, 1.0
	v_fmac_f32_e32 v52, v44, v52
	v_div_scale_f32 v44, vcc, 1.0, v49, 1.0
	v_mul_f32_e32 v48, v44, v52
	v_fma_f32 v50, -v51, v48, v44
	v_fmac_f32_e32 v48, v50, v52
	v_mul_f32_e32 v50, 0xbfb8aa3b, v42
	v_exp_f32_e32 v50, v50
	v_fma_f32 v44, -v51, v48, v44
	v_div_fmas_f32 v44, v44, v52, v48
	v_div_fixup_f32 v44, v44, v49, 1.0
	v_add_f32_e32 v48, 1.0, v50
	v_div_scale_f32 v50, s[38:39], v48, v48, 1.0
	v_rcp_f32_e32 v51, v50
	v_mul_f32_e32 v41, v41, v44
	v_mul_f32_e32 v41, v41, v45
	v_fma_f32 v44, -v50, v51, 1.0
	v_fmac_f32_e32 v51, v44, v51
	v_div_scale_f32 v44, vcc, 1.0, v48, 1.0
	v_mul_f32_e32 v45, v44, v51
	v_fma_f32 v49, -v50, v45, v44
	v_fmac_f32_e32 v45, v49, v51
	v_mul_f32_e32 v49, 0xbfb8aa3b, v43
	v_exp_f32_e32 v49, v49
	v_fma_f32 v44, -v50, v45, v44
	v_div_fmas_f32 v44, v44, v51, v45
	v_div_fixup_f32 v44, v44, v48, 1.0
	v_add_f32_e32 v45, 1.0, v49
	v_div_scale_f32 v49, s[38:39], v45, v45, 1.0
	v_rcp_f32_e32 v50, v49
	v_mul_f32_e32 v42, v42, v44
	v_mul_f32_e32 v42, v42, v46
	v_fma_f32 v44, -v49, v50, 1.0
	v_fmac_f32_e32 v50, v44, v50
	v_div_scale_f32 v44, vcc, 1.0, v45, 1.0
	v_mul_f32_e32 v46, v44, v50
	v_fma_f32 v48, -v49, v46, v44
	v_fmac_f32_e32 v46, v48, v50
	v_fma_f32 v44, -v49, v46, v44
	v_div_fmas_f32 v44, v44, v50, v46
	v_div_fixup_f32 v44, v44, v45, 1.0
	v_mul_f32_e32 v43, v43, v44
	v_cndmask_b32_e64 v44, v40, v42, s[6:7]
	v_mul_f32_e32 v43, v43, v47
	v_cndmask_b32_e64 v45, v41, v43, s[6:7]
	v_mov_b32_dpp v44, v44 quad_perm:[1,0,3,2] row_mask:0xf bank_mask:0xf bound_ctrl:1
	v_cndmask_b32_e64 v40, v44, v40, s[6:7]
	v_cndmask_b32_e64 v42, v42, v44, s[6:7]
	v_mul_f32_e32 v44, 0xbfb8aa3b, v32
	v_exp_f32_e32 v44, v44
	v_mov_b32_dpp v45, v45 quad_perm:[1,0,3,2] row_mask:0xf bank_mask:0xf bound_ctrl:1
	v_cvt_pk_bf16_f32 v40, v40, v42
	v_add_u32_e32 v42, 0x48000, v120
	v_cndmask_b32_e64 v41, v45, v41, s[6:7]
	v_cndmask_b32_e64 v43, v43, v45, s[6:7]
	v_add_u32_e32 v45, v42, v128
	global_store_dword v45, v40, s[20:21]
	v_cvt_pk_bf16_f32 v40, v41, v43
	v_add_f32_e32 v41, 1.0, v44
	v_div_scale_f32 v43, s[38:39], v41, v41, 1.0
	v_rcp_f32_e32 v44, v43
	v_add_u32_e32 v45, 0x48800, v120
	v_add_u32_e32 v46, v45, v128
	global_store_dword v46, v40, s[20:21]
	v_fma_f32 v40, -v43, v44, 1.0
	v_fmac_f32_e32 v44, v40, v44
	v_div_scale_f32 v40, vcc, 1.0, v41, 1.0
	v_mul_f32_e32 v46, v40, v44
	v_fma_f32 v47, -v43, v46, v40
	v_fmac_f32_e32 v46, v47, v44
	v_mul_f32_e32 v47, 0xbfb8aa3b, v33
	v_exp_f32_e32 v47, v47
	v_fma_f32 v40, -v43, v46, v40
	v_div_fmas_f32 v40, v40, v44, v46
	v_div_fixup_f32 v40, v40, v41, 1.0
	v_add_f32_e32 v43, 1.0, v47
	v_div_scale_f32 v44, s[38:39], v43, v43, 1.0
	v_rcp_f32_e32 v46, v44
	v_mul_f32_e32 v32, v32, v40
	v_mul_f32_e32 v32, v32, v36
	v_fma_f32 v36, -v44, v46, 1.0
	v_fmac_f32_e32 v46, v36, v46
	v_div_scale_f32 v36, vcc, 1.0, v43, 1.0
	v_mul_f32_e32 v40, v36, v46
	v_fma_f32 v41, -v44, v40, v36
	v_fmac_f32_e32 v40, v41, v46
	v_mul_f32_e32 v41, 0xbfb8aa3b, v34
	v_exp_f32_e32 v41, v41
	v_fma_f32 v36, -v44, v40, v36
	v_div_fmas_f32 v36, v36, v46, v40
	v_div_fixup_f32 v36, v36, v43, 1.0
	v_add_f32_e32 v40, 1.0, v41
	v_div_scale_f32 v41, s[38:39], v40, v40, 1.0
	v_rcp_f32_e32 v44, v41
	v_mul_f32_e32 v33, v33, v36
	v_mul_f32_e32 v33, v33, v37
	v_fma_f32 v36, -v41, v44, 1.0
	v_fmac_f32_e32 v44, v36, v44
	v_div_scale_f32 v36, vcc, 1.0, v40, 1.0
	v_mul_f32_e32 v37, v36, v44
	v_fma_f32 v43, -v41, v37, v36
	v_fmac_f32_e32 v37, v43, v44
	v_mul_f32_e32 v43, 0xbfb8aa3b, v35
	v_exp_f32_e32 v43, v43
	v_fma_f32 v36, -v41, v37, v36
	v_div_fmas_f32 v36, v36, v44, v37
	v_div_fixup_f32 v36, v36, v40, 1.0
	v_add_f32_e32 v37, 1.0, v43
	v_div_scale_f32 v41, s[38:39], v37, v37, 1.0
	v_rcp_f32_e32 v43, v41
	v_mul_f32_e32 v34, v34, v36
	v_mul_f32_e32 v34, v34, v38
	v_fma_f32 v36, -v41, v43, 1.0
	v_fmac_f32_e32 v43, v36, v43
	v_div_scale_f32 v36, vcc, 1.0, v37, 1.0
	v_mul_f32_e32 v38, v36, v43
	v_fma_f32 v40, -v41, v38, v36
	v_fmac_f32_e32 v38, v40, v43
	v_fma_f32 v36, -v41, v38, v36
	v_div_fmas_f32 v36, v36, v43, v38
	v_div_fixup_f32 v36, v36, v37, 1.0
	v_mul_f32_e32 v35, v35, v36
	v_mul_f32_e32 v35, v35, v39
	v_cndmask_b32_e64 v36, v32, v34, s[6:7]
	v_cndmask_b32_e64 v37, v33, v35, s[6:7]
	s_nop 0
	v_mov_b32_dpp v36, v36 quad_perm:[1,0,3,2] row_mask:0xf bank_mask:0xf bound_ctrl:1
	v_mov_b32_dpp v37, v37 quad_perm:[1,0,3,2] row_mask:0xf bank_mask:0xf bound_ctrl:1
	v_cndmask_b32_e64 v32, v36, v32, s[6:7]
	v_cndmask_b32_e64 v34, v34, v36, s[6:7]
	v_cndmask_b32_e64 v33, v37, v33, s[6:7]
	v_cndmask_b32_e64 v35, v35, v37, s[6:7]
	v_cvt_pk_bf16_f32 v32, v32, v34
	v_add_u32_e32 v34, v42, v112
	global_store_dword v34, v32, s[20:21]
	v_cvt_pk_bf16_f32 v32, v33, v35
	v_add_u32_e32 v33, v45, v112
	global_store_dword v33, v32, s[20:21]
	v_mul_f32_e32 v32, 0xbfb8aa3b, v24
	v_exp_f32_e32 v32, v32
	v_mul_f32_e32 v33, 0xbfb8aa3b, v25
	v_exp_f32_e32 v33, v33
	v_add_f32_e32 v32, 1.0, v32
	v_div_scale_f32 v34, s[38:39], v32, v32, 1.0
; DEVINL float sigm(float x) { return 1.f / (1.f + __expf(-x)); }
; template <int EPI, bool GATHER>
; DEVINL void gemm_tile(const Params& p, const u16* __restrict__ A, int lda, const int* __restrict__ rowidx,
;                       const u16* __restrict__ Bt, int ldb, int K, int brow, int bcol, int orow, int ocol) {
;     ...
;   const int row0 = orow + wr * 64 + fq * 4;
;   const int col0 = ocol + wc * 32 + fr;
;   const bool odd = (fr & 1) != 0;
;   const int colp = col0 - (odd ? 1 : 0);
; #pragma unroll
;   for (int ai = 0; ai < 2; ++ai)
; #pragma unroll
;     for (int m = 0; m < 4; ++m) {
;       const int rA = row0 + ai * HALF + m * 16 + (odd ? 2 : 0);
;       float gate[2] = {0.f, 0.f};
;       if (EPI == EPI_MOE2) { gate[0] = ((const float*)(ws + O_SELG))[rA]; gate[1] = ((const float*)(ws + O_SELG))[rA + 1]; }
; #pragma unroll
;       for (int bj = 0; bj < (EPI == EPI_HID ? 1 : 2); ++bj)
; #pragma unroll
;         for (int n = 0; n < 2; ++n) {
;           const int cc = bj * HALF + n * 16;
;           f32x4 v = acc[ai][bj][m][n];
;           if (EPI == EPI_HID) {
; #pragma unroll
;             for (int j = 0; j < 4; ++j) { const float a1 = acc[ai][0][m][n][j], a3 = acc[ai][1][m][n][j]; v[j] = a1 * sigm(a1) * a3; }
;           }
;           float lo[2], hi[2];
;           xchg_pairs(v, odd, lo, hi);
; #pragma unroll
;           for (int k = 0; k < 2; ++k) {
;             const unsigned row = (unsigned)(rA + k);
;             if (EPI == EPI_HID) {
;               *(unsigned*)(ws + O_HID + (row * 1024u + (unsigned)(colp + cc)) * 2u) = pk2(lo[k], hi[k]);
	v_rcp_f32_e32 v35, v34
	v_div_scale_f32 v36, vcc, 1.0, v32, 1.0
	v_add_f32_e32 v33, 1.0, v33
	v_fma_f32 v37, -v34, v35, 1.0
	v_fmac_f32_e32 v35, v37, v35
	v_mul_f32_e32 v37, v36, v35
	v_fma_f32 v38, -v34, v37, v36
	v_fmac_f32_e32 v37, v38, v35
	v_fma_f32 v34, -v34, v37, v36
	v_div_fmas_f32 v34, v34, v35, v37
	v_div_scale_f32 v35, s[38:39], v33, v33, 1.0
	v_rcp_f32_e32 v36, v35
	v_div_fixup_f32 v32, v34, v32, 1.0
	v_mul_f32_e32 v24, v24, v32
	v_mul_f32_e32 v24, v24, v28
	v_fma_f32 v28, -v35, v36, 1.0
	v_fmac_f32_e32 v36, v28, v36
	v_div_scale_f32 v28, vcc, 1.0, v33, 1.0
	v_mul_f32_e32 v32, v28, v36
	v_fma_f32 v34, -v35, v32, v28
	v_fmac_f32_e32 v32, v34, v36
	v_mul_f32_e32 v34, 0xbfb8aa3b, v26
	v_exp_f32_e32 v34, v34
	v_fma_f32 v28, -v35, v32, v28
	v_div_fmas_f32 v28, v28, v36, v32
	v_div_fixup_f32 v28, v28, v33, 1.0
	v_add_f32_e32 v32, 1.0, v34
	v_div_scale_f32 v34, s[38:39], v32, v32, 1.0
	v_rcp_f32_e32 v35, v34
	v_mul_f32_e32 v25, v25, v28
	v_mul_f32_e32 v25, v25, v29
	v_fma_f32 v28, -v34, v35, 1.0
	v_fmac_f32_e32 v35, v28, v35
	v_div_scale_f32 v28, vcc, 1.0, v32, 1.0
	v_mul_f32_e32 v29, v28, v35
	v_fma_f32 v33, -v34, v29, v28
	v_fmac_f32_e32 v29, v33, v35
	v_mul_f32_e32 v33, 0xbfb8aa3b, v27
	v_exp_f32_e32 v33, v33
	v_fma_f32 v28, -v34, v29, v28
	v_div_fmas_f32 v28, v28, v35, v29
	v_div_fixup_f32 v28, v28, v32, 1.0
	v_add_f32_e32 v29, 1.0, v33
	v_div_scale_f32 v33, s[38:39], v29, v29, 1.0
	v_rcp_f32_e32 v34, v33
	v_mul_f32_e32 v26, v26, v28
	v_mul_f32_e32 v26, v26, v30
	v_fma_f32 v28, -v33, v34, 1.0
	v_fmac_f32_e32 v34, v28, v34
	v_div_scale_f32 v28, vcc, 1.0, v29, 1.0
	v_mul_f32_e32 v30, v28, v34
	v_fma_f32 v32, -v33, v30, v28
	v_fmac_f32_e32 v30, v32, v34
	v_fma_f32 v28, -v33, v30, v28
	v_div_fmas_f32 v28, v28, v34, v30
	v_div_fixup_f32 v28, v28, v29, 1.0
	v_mul_f32_e32 v27, v27, v28
	v_cndmask_b32_e64 v28, v24, v26, s[6:7]
	v_mul_f32_e32 v27, v27, v31
	v_cndmask_b32_e64 v29, v25, v27, s[6:7]
	v_mov_b32_dpp v28, v28 quad_perm:[1,0,3,2] row_mask:0xf bank_mask:0xf bound_ctrl:1
	v_cndmask_b32_e64 v24, v28, v24, s[6:7]
	v_cndmask_b32_e64 v26, v26, v28, s[6:7]
	v_mul_f32_e32 v28, 0xbfb8aa3b, v16
	v_exp_f32_e32 v28, v28
	v_mov_b32_dpp v29, v29 quad_perm:[1,0,3,2] row_mask:0xf bank_mask:0xf bound_ctrl:1
	v_cvt_pk_bf16_f32 v24, v24, v26
	v_add_u32_e32 v26, 0x50000, v120
	v_cndmask_b32_e64 v25, v29, v25, s[6:7]
	v_cndmask_b32_e64 v27, v27, v29, s[6:7]
	v_add_u32_e32 v29, v26, v128
	global_store_dword v29, v24, s[20:21]
	v_cvt_pk_bf16_f32 v24, v25, v27
	v_add_f32_e32 v25, 1.0, v28
	v_div_scale_f32 v27, s[38:39], v25, v25, 1.0
	v_rcp_f32_e32 v28, v27
	v_add_u32_e32 v29, 0x50800, v120
	v_add_u32_e32 v30, v29, v128
	global_store_dword v30, v24, s[20:21]
	v_fma_f32 v24, -v27, v28, 1.0
	v_fmac_f32_e32 v28, v24, v28
	v_div_scale_f32 v24, vcc, 1.0, v25, 1.0
	v_mul_f32_e32 v30, v24, v28
	v_fma_f32 v31, -v27, v30, v24
	v_fmac_f32_e32 v30, v31, v28
	v_mul_f32_e32 v31, 0xbfb8aa3b, v17
	v_exp_f32_e32 v31, v31
	v_fma_f32 v24, -v27, v30, v24
	v_div_fmas_f32 v24, v24, v28, v30
	v_div_fixup_f32 v24, v24, v25, 1.0
	v_add_f32_e32 v27, 1.0, v31
	v_div_scale_f32 v28, s[38:39], v27, v27, 1.0
	v_rcp_f32_e32 v30, v28
	v_mul_f32_e32 v16, v16, v24
	v_mul_f32_e32 v16, v16, v20
	v_fma_f32 v20, -v28, v30, 1.0
	v_fmac_f32_e32 v30, v20, v30
	v_div_scale_f32 v20, vcc, 1.0, v27, 1.0
	v_mul_f32_e32 v24, v20, v30
	v_fma_f32 v25, -v28, v24, v20
	v_fmac_f32_e32 v24, v25, v30
	v_mul_f32_e32 v25, 0xbfb8aa3b, v18
	v_exp_f32_e32 v25, v25
	v_fma_f32 v20, -v28, v24, v20
	v_div_fmas_f32 v20, v20, v30, v24
	v_div_fixup_f32 v20, v20, v27, 1.0
	v_add_f32_e32 v24, 1.0, v25
	v_div_scale_f32 v25, s[38:39], v24, v24, 1.0
	v_rcp_f32_e32 v28, v25
	v_mul_f32_e32 v17, v17, v20
	v_mul_f32_e32 v17, v17, v21
	v_fma_f32 v20, -v25, v28, 1.0
	v_fmac_f32_e32 v28, v20, v28
	v_div_scale_f32 v20, vcc, 1.0, v24, 1.0
	v_mul_f32_e32 v21, v20, v28
	v_fma_f32 v27, -v25, v21, v20
	v_fmac_f32_e32 v21, v27, v28
	v_mul_f32_e32 v27, 0xbfb8aa3b, v19
	v_exp_f32_e32 v27, v27
	v_fma_f32 v20, -v25, v21, v20
	v_div_fmas_f32 v20, v20, v28, v21
	v_div_fixup_f32 v20, v20, v24, 1.0
	v_add_f32_e32 v21, 1.0, v27
	v_div_scale_f32 v25, s[38:39], v21, v21, 1.0
	v_rcp_f32_e32 v27, v25
	v_mul_f32_e32 v18, v18, v20
	v_mul_f32_e32 v18, v18, v22
	v_fma_f32 v20, -v25, v27, 1.0
	v_fmac_f32_e32 v27, v20, v27
	v_div_scale_f32 v20, vcc, 1.0, v21, 1.0
	v_mul_f32_e32 v22, v20, v27
	v_fma_f32 v24, -v25, v22, v20
	v_fmac_f32_e32 v22, v24, v27
	v_fma_f32 v20, -v25, v22, v20
	v_div_fmas_f32 v20, v20, v27, v22
	v_div_fixup_f32 v20, v20, v21, 1.0
	v_mul_f32_e32 v19, v19, v20
	v_mul_f32_e32 v19, v19, v23
	v_cndmask_b32_e64 v20, v16, v18, s[6:7]
	v_cndmask_b32_e64 v21, v17, v19, s[6:7]
	s_nop 0
	v_mov_b32_dpp v20, v20 quad_perm:[1,0,3,2] row_mask:0xf bank_mask:0xf bound_ctrl:1
	v_mov_b32_dpp v21, v21 quad_perm:[1,0,3,2] row_mask:0xf bank_mask:0xf bound_ctrl:1
	v_cndmask_b32_e64 v16, v20, v16, s[6:7]
	v_cndmask_b32_e64 v18, v18, v20, s[6:7]
	v_cndmask_b32_e64 v17, v21, v17, s[6:7]
	v_cndmask_b32_e64 v19, v19, v21, s[6:7]
	v_cvt_pk_bf16_f32 v16, v16, v18
	v_add_u32_e32 v18, v26, v112
	global_store_dword v18, v16, s[20:21]
	v_cvt_pk_bf16_f32 v16, v17, v19
	v_add_u32_e32 v17, v29, v112
	global_store_dword v17, v16, s[20:21]
	v_mul_f32_e32 v16, 0xbfb8aa3b, v8
	v_exp_f32_e32 v16, v16
; template <int EPI, bool GATHER>
; DEVINL void gemm_tile(const Params& p, const u16* __restrict__ A, int lda, const int* __restrict__ rowidx,
;                       const u16* __restrict__ Bt, int ldb, int K, int brow, int bcol, int orow, int ocol) {
;     ...
; #pragma unroll
;   for (int ai = 0; ai < 2; ++ai)
; #pragma unroll
;     for (int m = 0; m < 4; ++m) {
;       const int rA = row0 + ai * HALF + m * 16 + (odd ? 2 : 0);
;       float gate[2] = {0.f, 0.f};
;       if (EPI == EPI_MOE2) { gate[0] = ((const float*)(ws + O_SELG))[rA]; gate[1] = ((const float*)(ws + O_SELG))[rA + 1]; }
; #pragma unroll
;       for (int bj = 0; bj < (EPI == EPI_HID ? 1 : 2); ++bj)
; #pragma unroll
;         for (int n = 0; n < 2; ++n) {
;           const int cc = bj * HALF + n * 16;
;           f32x4 v = acc[ai][bj][m][n];
;           if (EPI == EPI_HID) {
; #pragma unroll
;             for (int j = 0; j < 4; ++j) { const float a1 = acc[ai][0][m][n][j], a3 = acc[ai][1][m][n][j]; v[j] = a1 * sigm(a1) * a3; }
;           }
;           float lo[2], hi[2];
;           xchg_pairs(v, odd, lo, hi);
; #pragma unroll
;           for (int k = 0; k < 2; ++k) {
;             const unsigned row = (unsigned)(rA + k);
;             if (EPI == EPI_HID) {
;               *(unsigned*)(ws + O_HID + (row * 1024u + (unsigned)(colp + cc)) * 2u) = pk2(lo[k], hi[k]);
;             } else if (EPI == EPI_COLS) {
;               *(unsigned*)(ws + O_COLS + (row * (unsigned)NCP + (unsigned)(colp + cc)) * 2u) = pk2(lo[k], hi[k]);
;             } else if (EPI == EPI_MOE2) {
;               *(unsigned*)(ws + O_EO + (row * 2048u + (unsigned)(colp + cc)) * 2u) = pk2(gate[k] * lo[k], gate[k] * hi[k]);
;             } else if (EPI == EPI_M1) {
;               const unsigned g2 = *(const unsigned*)(ws + O_COLS + (row * (unsigned)NCP + (unsigned)(C_GG + colp + cc)) * 2u);
;               *(unsigned*)(ws + O_M1 + (row * 2048u + (unsigned)(colp + cc)) * 2u) = pk2(sigm(bflo(g2)) * lo[k], sigm(bfhi(g2)) * hi[k]);
;             } else if (EPI == EPI_MERGED) {
;               const unsigned g2 = *(const unsigned*)(ws + O_COLS + (row * (unsigned)NCP + (unsigned)(C_GR + colp + cc)) * 2u);
;               const unsigned m1 = *(const unsigned*)(ws + O_M1 + (row * 2048u + (unsigned)(colp + cc)) * 2u);
;               *(unsigned*)(ws + O_MERGED + (row * 2048u + (unsigned)(colp + cc)) * 2u) =
	v_mul_f32_e32 v17, 0xbfb8aa3b, v9
	v_exp_f32_e32 v17, v17
	v_add_f32_e32 v16, 1.0, v16
	v_div_scale_f32 v18, s[38:39], v16, v16, 1.0
	v_rcp_f32_e32 v19, v18
	v_div_scale_f32 v20, vcc, 1.0, v16, 1.0
	v_add_f32_e32 v17, 1.0, v17
	v_fma_f32 v21, -v18, v19, 1.0
	v_fmac_f32_e32 v19, v21, v19
	v_mul_f32_e32 v21, v20, v19
	v_fma_f32 v22, -v18, v21, v20
	v_fmac_f32_e32 v21, v22, v19
	v_fma_f32 v18, -v18, v21, v20
	v_div_fmas_f32 v18, v18, v19, v21
	v_div_scale_f32 v19, s[38:39], v17, v17, 1.0
	v_rcp_f32_e32 v20, v19
	v_div_fixup_f32 v16, v18, v16, 1.0
	v_mul_f32_e32 v8, v8, v16
	v_mul_f32_e32 v8, v8, v12
	v_fma_f32 v12, -v19, v20, 1.0
	v_fmac_f32_e32 v20, v12, v20
	v_div_scale_f32 v12, vcc, 1.0, v17, 1.0
	v_mul_f32_e32 v16, v12, v20
	v_fma_f32 v18, -v19, v16, v12
	v_fmac_f32_e32 v16, v18, v20
	v_mul_f32_e32 v18, 0xbfb8aa3b, v10
	v_exp_f32_e32 v18, v18
	v_fma_f32 v12, -v19, v16, v12
	v_div_fmas_f32 v12, v12, v20, v16
	v_div_fixup_f32 v12, v12, v17, 1.0
	v_add_f32_e32 v16, 1.0, v18
	v_div_scale_f32 v18, s[38:39], v16, v16, 1.0
	v_rcp_f32_e32 v19, v18
	v_mul_f32_e32 v9, v9, v12
	v_mul_f32_e32 v9, v9, v13
	v_fma_f32 v12, -v18, v19, 1.0
	v_fmac_f32_e32 v19, v12, v19
	v_div_scale_f32 v12, vcc, 1.0, v16, 1.0
	v_mul_f32_e32 v13, v12, v19
	v_fma_f32 v17, -v18, v13, v12
	v_fmac_f32_e32 v13, v17, v19
	v_mul_f32_e32 v17, 0xbfb8aa3b, v11
	v_exp_f32_e32 v17, v17
	v_fma_f32 v12, -v18, v13, v12
	v_div_fmas_f32 v12, v12, v19, v13
	v_div_fixup_f32 v12, v12, v16, 1.0
	v_add_f32_e32 v13, 1.0, v17
	v_div_scale_f32 v17, s[38:39], v13, v13, 1.0
	v_rcp_f32_e32 v18, v17
	v_mul_f32_e32 v10, v10, v12
	v_mul_f32_e32 v10, v10, v14
	v_fma_f32 v12, -v17, v18, 1.0
	v_fmac_f32_e32 v18, v12, v18
	v_div_scale_f32 v12, vcc, 1.0, v13, 1.0
	v_mul_f32_e32 v14, v12, v18
	v_fma_f32 v16, -v17, v14, v12
	v_fmac_f32_e32 v14, v16, v18
	v_fma_f32 v12, -v17, v14, v12
	v_div_fmas_f32 v12, v12, v18, v14
	v_div_fixup_f32 v12, v12, v13, 1.0
	v_mul_f32_e32 v11, v11, v12
	v_cndmask_b32_e64 v12, v8, v10, s[6:7]
	v_mul_f32_e32 v11, v11, v15
	v_cndmask_b32_e64 v13, v9, v11, s[6:7]
	v_mov_b32_dpp v12, v12 quad_perm:[1,0,3,2] row_mask:0xf bank_mask:0xf bound_ctrl:1
	v_cndmask_b32_e64 v8, v12, v8, s[6:7]
	v_cndmask_b32_e64 v10, v10, v12, s[6:7]
	v_mul_f32_e32 v12, 0xbfb8aa3b, v0
	v_exp_f32_e32 v12, v12
	v_mov_b32_dpp v13, v13 quad_perm:[1,0,3,2] row_mask:0xf bank_mask:0xf bound_ctrl:1
	v_cvt_pk_bf16_f32 v8, v8, v10
	v_add_u32_e32 v10, 0x58000, v120
	v_cndmask_b32_e64 v9, v13, v9, s[6:7]
	v_cndmask_b32_e64 v11, v11, v13, s[6:7]
	v_add_u32_e32 v13, v10, v128
	global_store_dword v13, v8, s[20:21]
	v_cvt_pk_bf16_f32 v8, v9, v11
	v_add_f32_e32 v9, 1.0, v12
	v_div_scale_f32 v11, s[38:39], v9, v9, 1.0
	v_rcp_f32_e32 v12, v11
	v_add_u32_e32 v13, 0x58800, v120
	v_add_u32_e32 v14, v13, v128
	global_store_dword v14, v8, s[20:21]
	v_fma_f32 v8, -v11, v12, 1.0
	v_fmac_f32_e32 v12, v8, v12
	v_div_scale_f32 v8, vcc, 1.0, v9, 1.0
	v_mul_f32_e32 v14, v8, v12
	v_fma_f32 v15, -v11, v14, v8
	v_fmac_f32_e32 v14, v15, v12
	v_mul_f32_e32 v15, 0xbfb8aa3b, v1
	v_exp_f32_e32 v15, v15
	v_fma_f32 v8, -v11, v14, v8
	v_div_fmas_f32 v8, v8, v12, v14
	v_div_fixup_f32 v8, v8, v9, 1.0
	v_add_f32_e32 v11, 1.0, v15
	v_div_scale_f32 v12, s[38:39], v11, v11, 1.0
	v_rcp_f32_e32 v14, v12
	v_mul_f32_e32 v0, v0, v8
	v_mul_f32_e32 v0, v0, v4
	v_fma_f32 v4, -v12, v14, 1.0
	v_fmac_f32_e32 v14, v4, v14
	v_div_scale_f32 v4, vcc, 1.0, v11, 1.0
	v_mul_f32_e32 v8, v4, v14
	v_fma_f32 v9, -v12, v8, v4
	v_fmac_f32_e32 v8, v9, v14
	v_mul_f32_e32 v9, 0xbfb8aa3b, v2
	v_exp_f32_e32 v9, v9
	v_fma_f32 v4, -v12, v8, v4
	v_div_fmas_f32 v4, v4, v14, v8
	v_div_fixup_f32 v4, v4, v11, 1.0
	v_add_f32_e32 v8, 1.0, v9
	v_div_scale_f32 v9, s[38:39], v8, v8, 1.0
	v_rcp_f32_e32 v12, v9
	v_mul_f32_e32 v1, v1, v4
	v_mul_f32_e32 v1, v1, v5
	v_fma_f32 v4, -v9, v12, 1.0
	v_fmac_f32_e32 v12, v4, v12
	v_div_scale_f32 v4, vcc, 1.0, v8, 1.0
	v_mul_f32_e32 v5, v4, v12
	v_fma_f32 v11, -v9, v5, v4
	v_fmac_f32_e32 v5, v11, v12
	v_mul_f32_e32 v11, 0xbfb8aa3b, v3
	v_exp_f32_e32 v11, v11
	v_fma_f32 v4, -v9, v5, v4
	v_div_fmas_f32 v4, v4, v12, v5
	v_div_fixup_f32 v4, v4, v8, 1.0
	v_add_f32_e32 v5, 1.0, v11
	v_div_scale_f32 v9, s[38:39], v5, v5, 1.0
	v_rcp_f32_e32 v11, v9
	v_mul_f32_e32 v2, v2, v4
	v_mul_f32_e32 v2, v2, v6
	v_fma_f32 v4, -v9, v11, 1.0
	v_fmac_f32_e32 v11, v4, v11
	v_div_scale_f32 v4, vcc, 1.0, v5, 1.0
	v_mul_f32_e32 v6, v4, v11
	v_fma_f32 v8, -v9, v6, v4
	v_fmac_f32_e32 v6, v8, v11
	v_fma_f32 v4, -v9, v6, v4
	v_div_fmas_f32 v4, v4, v11, v6
	v_div_fixup_f32 v4, v4, v5, 1.0
	v_mul_f32_e32 v3, v3, v4
	v_mul_f32_e32 v3, v3, v7
	v_cndmask_b32_e64 v4, v0, v2, s[6:7]
	v_cndmask_b32_e64 v5, v1, v3, s[6:7]
	s_nop 0
	v_mov_b32_dpp v4, v4 quad_perm:[1,0,3,2] row_mask:0xf bank_mask:0xf bound_ctrl:1
	v_mov_b32_dpp v5, v5 quad_perm:[1,0,3,2] row_mask:0xf bank_mask:0xf bound_ctrl:1
	v_cndmask_b32_e64 v0, v4, v0, s[6:7]
	v_cndmask_b32_e64 v2, v2, v4, s[6:7]
	v_cndmask_b32_e64 v1, v5, v1, s[6:7]
	v_cndmask_b32_e64 v3, v3, v5, s[6:7]
	v_cvt_pk_bf16_f32 v0, v0, v2
	v_add_u32_e32 v2, v10, v112
	global_store_dword v2, v0, s[20:21]
	v_cvt_pk_bf16_f32 v0, v1, v3
	v_add_u32_e32 v1, v13, v112
	global_store_dword v1, v0, s[20:21]
	s_add_i32 s46, s46, s94
	s_add_i32 s45, s45, s94
	s_cmpk_lt_i32 s46, 0x200
	s_nop 0
	s_barrier
	s_cbranch_scc0 .LBB0_976
